# plus: s_setprio 1 hoisted above the barrier that opens each GEMM MFMA phase
# baseline (speedup 1.0000x reference)
; #define PG8_STAGE(bufoff, gbase, voff) do { _Pragma("unroll") for (int _i = 0; _i < 2; ++_i) \
;         __builtin_amdgcn_global_load_lds((const unsigned*)((const char*)(gbase) + (voff)[_i]), (PG8_LAS unsigned*)(lds + (bufoff) + ldsw + _i * 8192), 16, 0, 0); } while (0)
; #define PG8_LDA(dst, b, h) do { _Pragma("unroll") for (int m = 0; m < 4; ++m) _Pragma("unroll") for (int k = 0; k < 2; ++k) dst[m][k] = *(const PG8_LAS bf16x8*)(lds + PG8_SA(b, h) + aoff + m * 2048 + k * 1024); } while (0)
; #define PG8_LDB(dst, b, h) do { _Pragma("unroll") for (int n = 0; n < 2; ++n) _Pragma("unroll") for (int k = 0; k < 2; ++k) dst[n][k] = *(const PG8_LAS bf16x8*)(lds + PG8_SB(b, h) + boff + n * 2048 + k * 1024); } while (0)
; #define PG8_MMA(ai, bj, At, Bt) do { __builtin_amdgcn_s_setprio(1); _Pragma("unroll") for (int m = 0; m < 4; ++m) _Pragma("unroll") for (int n = 0; n < 2; ++n) _Pragma("unroll") for (int k = 0; k < 2; ++k) \
;         acc[ai][bj][m][n] = __builtin_amdgcn_mfma_f32_16x16x32_bf16(Bt[n][k], At[m][k], acc[ai][bj][m][n], 0, 0, 0); __builtin_amdgcn_s_setprio(0); } while (0)
; #define PG8_WAIT_V(n) asm volatile("s_waitcnt vmcnt(" #n ")" ::: "memory")
; #define PG8_WAIT_L(n) asm volatile("s_waitcnt lgkmcnt(" #n ")" ::: "memory")
; template <class Epi, class Sched, bool ALIGN_EPI = false, bool SP2 = false>
; __device__ __forceinline__ void gemm_phase(PG8_LAS unsigned char* lds, const Gemm g, const Sched& S, const Epi& E, const int tid) {
;     ...
;             const bool last = (t == nt - 2);
;             const char* a1 = cA + (size_t)(t + 1) * kstep;
;             const char* a2 = last ? nA : cA + (size_t)(t + 2) * kstep; const char* b2 = last ? nB : cB + (size_t)(t + 2) * kstep;
;             const char* a3 = a2 + kstep; const char* b3 = b2 + kstep;
;             if (last && has_next) S.a_ready(nxt);
;             if constexpr (SP2) {
;             PG8_LDB(B0, 0, 0); PG8_LDB(B1, 0, 1); PG8_SCHED; PG8_LDA(At, 0, 0); PG8_STAGE(PG8_SA(1, 1), a1 + hstepA, voffA);
;             PG8_WAIT_V(8); PG8_WAIT_L(0); PG8_BAR; PG8_MMA(0, 0, At, B0); PG8_MMA(0, 1, At, B1); PG8_BAR; PG8_SCHED;
;             PG8_LDA(At, 0, 1); PG8_STAGE(PG8_SB(0, 0), b2, voffB); PG8_STAGE(PG8_SB(0, 1), b2 + hstepB, voffB); PG8_STAGE(PG8_SA(0, 0), a2, voffA);
;             PG8_WAIT_V(8); PG8_WAIT_L(0); PG8_BAR; PG8_MMA(1, 0, At, B0); PG8_MMA(1, 1, At, B1); PG8_BAR; PG8_SCHED;
.LBB0_36:
	s_add_u32 s24, s46, 0xfffc0080
	s_addc_u32 s25, s47, -1
	s_add_i32 s63, 0, 0x10000
	s_cmp_eq_u32 s59, 12
	s_cselect_b32 s51, s19, s25
	s_cselect_b32 s50, s53, s24
	s_cselect_b32 s49, s15, s58
	s_cselect_b32 s48, s54, s55
	s_add_i32 s65, 0, 0x14000
	v_add_u32_e32 v154, s63, v143
	v_add_u32_e32 v170, s65, v143
	ds_read_b128 v[138:141], v154
	ds_read_b128 v[146:149], v154 offset:1024
	ds_read_b128 v[150:153], v154 offset:2048
	ds_read_b128 v[154:157], v154 offset:3072
	ds_read_b128 v[158:161], v170
	ds_read_b128 v[162:165], v170 offset:1024
	ds_read_b128 v[166:169], v170 offset:2048
	ds_read_b128 v[170:173], v170 offset:3072
	v_lshl_add_u64 v[190:191], s[46:47], 0, v[136:137]
	s_add_i32 m0, s23, 0xc000
	ds_read_b128 v[174:177], v145
	ds_read_b128 v[178:181], v145 offset:1024
	ds_read_b128 v[182:185], v145 offset:2048
	ds_read_b128 v[186:189], v145 offset:3072
	ds_read_b128 v[200:203], v145 offset:4096
	ds_read_b128 v[204:207], v145 offset:5120
	ds_read_b128 v[208:211], v145 offset:6144
	ds_read_b128 v[212:215], v145 offset:7168
	global_load_lds_dwordx4 v[190:191], off
	v_lshl_add_u64 v[190:191], s[46:47], 0, v[134:135]
	s_add_i32 m0, s23, 0xe000
	s_nop 0
	global_load_lds_dwordx4 v[190:191], off
	s_waitcnt vmcnt(8) lgkmcnt(0)
	s_setprio 1
	s_barrier
	v_mfma_f32_16x16x32_bf16 v[124:127], v[138:141], v[174:177], v[124:127]
	v_mfma_f32_16x16x32_bf16 v[120:123], v[150:153], v[174:177], v[120:123]
	v_mfma_f32_16x16x32_bf16 v[108:111], v[138:141], v[182:185], v[108:111]
	v_mfma_f32_16x16x32_bf16 v[104:107], v[150:153], v[182:185], v[104:107]
	v_mfma_f32_16x16x32_bf16 v[92:95], v[138:141], v[200:203], v[92:95]
	v_mfma_f32_16x16x32_bf16 v[88:91], v[150:153], v[200:203], v[88:91]
	v_mfma_f32_16x16x32_bf16 v[76:79], v[138:141], v[208:211], v[76:79]
	v_mfma_f32_16x16x32_bf16 v[72:75], v[150:153], v[208:211], v[72:75]
	v_mfma_f32_16x16x32_bf16 v[124:127], v[146:149], v[178:181], v[124:127]
	v_mfma_f32_16x16x32_bf16 v[120:123], v[154:157], v[178:181], v[120:123]
	v_mfma_f32_16x16x32_bf16 v[108:111], v[146:149], v[186:189], v[108:111]
	v_mfma_f32_16x16x32_bf16 v[104:107], v[154:157], v[186:189], v[104:107]
	v_mfma_f32_16x16x32_bf16 v[92:95], v[146:149], v[204:207], v[92:95]
	v_mfma_f32_16x16x32_bf16 v[88:91], v[154:157], v[204:207], v[88:91]
	v_mfma_f32_16x16x32_bf16 v[76:79], v[146:149], v[212:215], v[76:79]
	v_mfma_f32_16x16x32_bf16 v[72:75], v[154:157], v[212:215], v[72:75]
	s_setprio 0
	s_setprio 1
	v_mfma_f32_16x16x32_bf16 v[116:119], v[158:161], v[174:177], v[116:119]
	v_mfma_f32_16x16x32_bf16 v[112:115], v[166:169], v[174:177], v[112:115]
	v_mfma_f32_16x16x32_bf16 v[100:103], v[158:161], v[182:185], v[100:103]
	v_mfma_f32_16x16x32_bf16 v[96:99], v[166:169], v[182:185], v[96:99]
	v_mfma_f32_16x16x32_bf16 v[84:87], v[158:161], v[200:203], v[84:87]
	v_mfma_f32_16x16x32_bf16 v[80:83], v[166:169], v[200:203], v[80:83]
	v_mfma_f32_16x16x32_bf16 v[68:71], v[158:161], v[208:211], v[68:71]
	v_mfma_f32_16x16x32_bf16 v[64:67], v[166:169], v[208:211], v[64:67]
	v_mfma_f32_16x16x32_bf16 v[116:119], v[162:165], v[178:181], v[116:119]
	v_mfma_f32_16x16x32_bf16 v[112:115], v[170:173], v[178:181], v[112:115]
	v_mfma_f32_16x16x32_bf16 v[100:103], v[162:165], v[186:189], v[100:103]
	v_mfma_f32_16x16x32_bf16 v[96:99], v[170:173], v[186:189], v[96:99]
	v_mfma_f32_16x16x32_bf16 v[84:87], v[162:165], v[204:207], v[84:87]
	v_mfma_f32_16x16x32_bf16 v[80:83], v[170:173], v[204:207], v[80:83]
	v_mfma_f32_16x16x32_bf16 v[68:71], v[162:165], v[212:215], v[68:71]
	v_mfma_f32_16x16x32_bf16 v[64:67], v[170:173], v[212:215], v[64:67]
	s_setprio 0
	s_barrier
	s_add_i32 s24, s63, s21
	v_lshl_add_u64 v[190:191], s[48:49], 0, v[192:193]
	s_mov_b32 m0, s24
	ds_read_b128 v[174:177], v145 offset:16384
	ds_read_b128 v[178:181], v145 offset:17408
	ds_read_b128 v[182:185], v145 offset:18432
	ds_read_b128 v[186:189], v145 offset:19456
	ds_read_b128 v[200:203], v145 offset:20480
	ds_read_b128 v[204:207], v145 offset:21504
	ds_read_b128 v[208:211], v145 offset:22528
	ds_read_b128 v[212:215], v145 offset:23552
	global_load_lds_dwordx4 v[190:191], off
	s_add_i32 m0, s24, 0x2000
	s_add_u32 s24, s48, 0x40000
	v_lshl_add_u64 v[216:217], s[48:49], 0, v[128:129]
	s_addc_u32 s25, s49, 0
	s_add_i32 s63, s65, s21
	global_load_lds_dwordx4 v[216:217], off
	v_lshl_add_u64 v[218:219], s[24:25], 0, v[192:193]
	s_mov_b32 m0, s63
	v_lshl_add_u64 v[220:221], s[50:51], 0, v[130:131]
	global_load_lds_dwordx4 v[218:219], off
	v_lshl_add_u64 v[218:219], s[24:25], 0, v[128:129]
	s_add_i32 m0, s63, 0x2000
	s_nop 0
	global_load_lds_dwordx4 v[218:219], off
	v_lshl_add_u64 v[218:219], s[50:51], 0, v[132:133]
	s_mov_b32 m0, s23
	s_nop 0
	global_load_lds_dwordx4 v[218:219], off
	s_mov_b32 m0, s26
	s_nop 0
	global_load_lds_dwordx4 v[220:221], off
	s_waitcnt vmcnt(8) lgkmcnt(0)
	s_setprio 1
	s_barrier
; #define PG8_STAGE(bufoff, gbase, voff) do { _Pragma("unroll") for (int _i = 0; _i < 2; ++_i) \
;         __builtin_amdgcn_global_load_lds((const unsigned*)((const char*)(gbase) + (voff)[_i]), (PG8_LAS unsigned*)(lds + (bufoff) + ldsw + _i * 8192), 16, 0, 0); } while (0)
; #define PG8_LDA(dst, b, h) do { _Pragma("unroll") for (int m = 0; m < 4; ++m) _Pragma("unroll") for (int k = 0; k < 2; ++k) dst[m][k] = *(const PG8_LAS bf16x8*)(lds + PG8_SA(b, h) + aoff + m * 2048 + k * 1024); } while (0)
; #define PG8_LDB(dst, b, h) do { _Pragma("unroll") for (int n = 0; n < 2; ++n) _Pragma("unroll") for (int k = 0; k < 2; ++k) dst[n][k] = *(const PG8_LAS bf16x8*)(lds + PG8_SB(b, h) + boff + n * 2048 + k * 1024); } while (0)
; #define PG8_MMA(ai, bj, At, Bt) do { __builtin_amdgcn_s_setprio(1); _Pragma("unroll") for (int m = 0; m < 4; ++m) _Pragma("unroll") for (int n = 0; n < 2; ++n) _Pragma("unroll") for (int k = 0; k < 2; ++k) \
;         acc[ai][bj][m][n] = __builtin_amdgcn_mfma_f32_16x16x32_bf16(Bt[n][k], At[m][k], acc[ai][bj][m][n], 0, 0, 0); __builtin_amdgcn_s_setprio(0); } while (0)
; #define PG8_WAIT_V(n) asm volatile("s_waitcnt vmcnt(" #n ")" ::: "memory")
; #define PG8_WAIT_L(n) asm volatile("s_waitcnt lgkmcnt(" #n ")" ::: "memory")
; #define PG8_BAR __builtin_amdgcn_s_barrier()
; #define PG8_SCHED __builtin_amdgcn_sched_barrier(0)
; template <class Epi, class Sched, bool ALIGN_EPI = false, bool SP2 = false>
; __device__ __forceinline__ void gemm_phase(PG8_LAS unsigned char* lds, const Gemm g, const Sched& S, const Epi& E, const int tid) {
;     ...
;             PG8_WAIT_V(8); PG8_WAIT_L(0); PG8_BAR; PG8_MMA(1, 0, At, B0); PG8_MMA(1, 1, At, B1); PG8_BAR; PG8_SCHED;
;             PG8_LDB(B0, 1, 0); PG8_LDB(B1, 1, 1); PG8_SCHED; PG8_LDA(At, 1, 0); PG8_STAGE(PG8_SA(0, 1), a2 + hstepA, voffA);
;             PG8_WAIT_V(8); PG8_WAIT_L(0); PG8_BAR; PG8_MMA(0, 0, At, B0); PG8_MMA(0, 1, At, B1); PG8_BAR; PG8_SCHED;
	v_mfma_f32_16x16x32_bf16 v[60:63], v[138:141], v[174:177], v[60:63]
	v_mfma_f32_16x16x32_bf16 v[56:59], v[150:153], v[174:177], v[56:59]
	v_mfma_f32_16x16x32_bf16 v[44:47], v[138:141], v[182:185], v[44:47]
	v_mfma_f32_16x16x32_bf16 v[40:43], v[150:153], v[182:185], v[40:43]
	v_mfma_f32_16x16x32_bf16 v[28:31], v[138:141], v[200:203], v[28:31]
	v_mfma_f32_16x16x32_bf16 v[24:27], v[150:153], v[200:203], v[24:27]
	v_mfma_f32_16x16x32_bf16 v[12:15], v[138:141], v[208:211], v[12:15]
	v_mfma_f32_16x16x32_bf16 v[8:11], v[150:153], v[208:211], v[8:11]
	v_mfma_f32_16x16x32_bf16 v[60:63], v[146:149], v[178:181], v[60:63]
	v_mfma_f32_16x16x32_bf16 v[56:59], v[154:157], v[178:181], v[56:59]
	v_mfma_f32_16x16x32_bf16 v[44:47], v[146:149], v[186:189], v[44:47]
	v_mfma_f32_16x16x32_bf16 v[40:43], v[154:157], v[186:189], v[40:43]
	v_mfma_f32_16x16x32_bf16 v[28:31], v[146:149], v[204:207], v[28:31]
	v_mfma_f32_16x16x32_bf16 v[24:27], v[154:157], v[204:207], v[24:27]
	v_mfma_f32_16x16x32_bf16 v[12:15], v[146:149], v[212:215], v[12:15]
	v_mfma_f32_16x16x32_bf16 v[8:11], v[154:157], v[212:215], v[8:11]
	s_setprio 0
	s_setprio 1
	v_mfma_f32_16x16x32_bf16 v[52:55], v[158:161], v[174:177], v[52:55]
	v_mfma_f32_16x16x32_bf16 v[48:51], v[166:169], v[174:177], v[48:51]
	v_mfma_f32_16x16x32_bf16 v[36:39], v[158:161], v[182:185], v[36:39]
	v_mfma_f32_16x16x32_bf16 v[32:35], v[166:169], v[182:185], v[32:35]
	v_mfma_f32_16x16x32_bf16 v[20:23], v[158:161], v[200:203], v[20:23]
	v_mfma_f32_16x16x32_bf16 v[16:19], v[166:169], v[200:203], v[16:19]
	v_mfma_f32_16x16x32_bf16 v[4:7], v[158:161], v[208:211], v[4:7]
	v_mfma_f32_16x16x32_bf16 v[0:3], v[166:169], v[208:211], v[0:3]
	v_mfma_f32_16x16x32_bf16 v[52:55], v[162:165], v[178:181], v[52:55]
	v_mfma_f32_16x16x32_bf16 v[48:51], v[170:173], v[178:181], v[48:51]
	v_mfma_f32_16x16x32_bf16 v[36:39], v[162:165], v[186:189], v[36:39]
	v_mfma_f32_16x16x32_bf16 v[32:35], v[170:173], v[186:189], v[32:35]
	v_mfma_f32_16x16x32_bf16 v[20:23], v[162:165], v[204:207], v[20:23]
	v_mfma_f32_16x16x32_bf16 v[16:19], v[170:173], v[204:207], v[16:19]
	v_mfma_f32_16x16x32_bf16 v[4:7], v[162:165], v[212:215], v[4:7]
	v_mfma_f32_16x16x32_bf16 v[0:3], v[170:173], v[212:215], v[0:3]
	s_setprio 0
	s_barrier
	s_add_i32 s63, 0, 0x18000
	s_add_i32 s65, 0, 0x1c000
	v_add_u32_e32 v154, s63, v143
	v_add_u32_e32 v170, s65, v143
	ds_read_b128 v[138:141], v154
	ds_read_b128 v[146:149], v154 offset:1024
	ds_read_b128 v[150:153], v154 offset:2048
	ds_read_b128 v[154:157], v154 offset:3072
	ds_read_b128 v[158:161], v170
	ds_read_b128 v[162:165], v170 offset:1024
	ds_read_b128 v[166:169], v170 offset:2048
	ds_read_b128 v[170:173], v170 offset:3072
	s_add_u32 s24, s50, 0x40000
	s_addc_u32 s25, s51, 0
	s_mov_b32 m0, s27
	v_lshl_add_u64 v[222:223], s[24:25], 0, v[132:133]
	ds_read_b128 v[174:177], v145 offset:32768
	ds_read_b128 v[178:181], v145 offset:33792
	ds_read_b128 v[182:185], v145 offset:34816
	ds_read_b128 v[186:189], v145 offset:35840
	ds_read_b128 v[200:203], v145 offset:36864
	ds_read_b128 v[204:207], v145 offset:37888
	ds_read_b128 v[208:211], v145 offset:38912
	ds_read_b128 v[212:215], v145 offset:39936
	global_load_lds_dwordx4 v[222:223], off
	v_lshl_add_u64 v[222:223], s[24:25], 0, v[130:131]
	s_mov_b32 m0, s28
	s_nop 0
	global_load_lds_dwordx4 v[222:223], off
	s_waitcnt vmcnt(8) lgkmcnt(0)
	s_setprio 1
	s_barrier
	v_mfma_f32_16x16x32_bf16 v[124:127], v[138:141], v[174:177], v[124:127]
	v_mfma_f32_16x16x32_bf16 v[120:123], v[150:153], v[174:177], v[120:123]
	v_mfma_f32_16x16x32_bf16 v[108:111], v[138:141], v[182:185], v[108:111]
	v_mfma_f32_16x16x32_bf16 v[104:107], v[150:153], v[182:185], v[104:107]
	v_mfma_f32_16x16x32_bf16 v[92:95], v[138:141], v[200:203], v[92:95]
	v_mfma_f32_16x16x32_bf16 v[88:91], v[150:153], v[200:203], v[88:91]
	v_mfma_f32_16x16x32_bf16 v[76:79], v[138:141], v[208:211], v[76:79]
	v_mfma_f32_16x16x32_bf16 v[72:75], v[150:153], v[208:211], v[72:75]
	v_mfma_f32_16x16x32_bf16 v[124:127], v[146:149], v[178:181], v[124:127]
	v_mfma_f32_16x16x32_bf16 v[120:123], v[154:157], v[178:181], v[120:123]
	v_mfma_f32_16x16x32_bf16 v[108:111], v[146:149], v[186:189], v[108:111]
	v_mfma_f32_16x16x32_bf16 v[104:107], v[154:157], v[186:189], v[104:107]
	v_mfma_f32_16x16x32_bf16 v[92:95], v[146:149], v[204:207], v[92:95]
	v_mfma_f32_16x16x32_bf16 v[88:91], v[154:157], v[204:207], v[88:91]
	v_mfma_f32_16x16x32_bf16 v[76:79], v[146:149], v[212:215], v[76:79]
	v_mfma_f32_16x16x32_bf16 v[72:75], v[154:157], v[212:215], v[72:75]
	s_setprio 0
	s_setprio 1
	v_mfma_f32_16x16x32_bf16 v[116:119], v[158:161], v[174:177], v[116:119]
	v_mfma_f32_16x16x32_bf16 v[112:115], v[166:169], v[174:177], v[112:115]
	v_mfma_f32_16x16x32_bf16 v[100:103], v[158:161], v[182:185], v[100:103]
	v_mfma_f32_16x16x32_bf16 v[96:99], v[166:169], v[182:185], v[96:99]
	v_mfma_f32_16x16x32_bf16 v[84:87], v[158:161], v[200:203], v[84:87]
	v_mfma_f32_16x16x32_bf16 v[80:83], v[166:169], v[200:203], v[80:83]
	v_mfma_f32_16x16x32_bf16 v[68:71], v[158:161], v[208:211], v[68:71]
	v_mfma_f32_16x16x32_bf16 v[64:67], v[166:169], v[208:211], v[64:67]
	v_mfma_f32_16x16x32_bf16 v[116:119], v[162:165], v[178:181], v[116:119]
	v_mfma_f32_16x16x32_bf16 v[112:115], v[170:173], v[178:181], v[112:115]
	v_mfma_f32_16x16x32_bf16 v[100:103], v[162:165], v[186:189], v[100:103]
	v_mfma_f32_16x16x32_bf16 v[96:99], v[170:173], v[186:189], v[96:99]
	v_mfma_f32_16x16x32_bf16 v[84:87], v[162:165], v[204:207], v[84:87]
	v_mfma_f32_16x16x32_bf16 v[80:83], v[170:173], v[204:207], v[80:83]
	v_mfma_f32_16x16x32_bf16 v[68:71], v[162:165], v[212:215], v[68:71]
	v_mfma_f32_16x16x32_bf16 v[64:67], v[170:173], v[212:215], v[64:67]
	s_setprio 0
	s_barrier
; #define PG8_STAGE(bufoff, gbase, voff) do { _Pragma("unroll") for (int _i = 0; _i < 2; ++_i) \
;         __builtin_amdgcn_global_load_lds((const unsigned*)((const char*)(gbase) + (voff)[_i]), (PG8_LAS unsigned*)(lds + (bufoff) + ldsw + _i * 8192), 16, 0, 0); } while (0)
; #define PG8_LDA(dst, b, h) do { _Pragma("unroll") for (int m = 0; m < 4; ++m) _Pragma("unroll") for (int k = 0; k < 2; ++k) dst[m][k] = *(const PG8_LAS bf16x8*)(lds + PG8_SA(b, h) + aoff + m * 2048 + k * 1024); } while (0)
; #define PG8_MMA(ai, bj, At, Bt) do { __builtin_amdgcn_s_setprio(1); _Pragma("unroll") for (int m = 0; m < 4; ++m) _Pragma("unroll") for (int n = 0; n < 2; ++n) _Pragma("unroll") for (int k = 0; k < 2; ++k) \
;         acc[ai][bj][m][n] = __builtin_amdgcn_mfma_f32_16x16x32_bf16(Bt[n][k], At[m][k], acc[ai][bj][m][n], 0, 0, 0); __builtin_amdgcn_s_setprio(0); } while (0)
; #define PG8_WAIT_V(n) asm volatile("s_waitcnt vmcnt(" #n ")" ::: "memory")
; #define PG8_WAIT_L(n) asm volatile("s_waitcnt lgkmcnt(" #n ")" ::: "memory")
; #define PG8_BAR __builtin_amdgcn_s_barrier()
; #define PG8_SCHED __builtin_amdgcn_sched_barrier(0)
; template <class Epi, class Sched, bool ALIGN_EPI = false, bool SP2 = false>
; __device__ __forceinline__ void gemm_phase(PG8_LAS unsigned char* lds, const Gemm g, const Sched& S, const Epi& E, const int tid) {
;     ...
;             PG8_LDA(At, 1, 1); PG8_STAGE(PG8_SB(1, 0), b3, voffB); PG8_STAGE(PG8_SB(1, 1), b3 + hstepB, voffB); PG8_STAGE(PG8_SA(1, 0), a3, voffA);
;             PG8_WAIT_V(8); PG8_WAIT_L(0); PG8_BAR; PG8_MMA(1, 0, At, B0); PG8_MMA(1, 1, At, B1); PG8_BAR; PG8_SCHED;
;     ...
;         if constexpr (ALIGN_EPI) { if (wr == 0) PG8_BAR; }
	s_add_i32 s24, s63, s21
	v_lshl_add_u64 v[190:191], v[190:191], 0, s[60:61]
	s_mov_b32 m0, s24
	ds_read_b128 v[174:177], v145 offset:49152
	ds_read_b128 v[178:181], v145 offset:50176
	ds_read_b128 v[182:185], v145 offset:51200
	ds_read_b128 v[186:189], v145 offset:52224
	ds_read_b128 v[200:203], v145 offset:53248
	ds_read_b128 v[204:207], v145 offset:54272
	ds_read_b128 v[208:211], v145 offset:55296
	ds_read_b128 v[212:215], v145 offset:56320
	global_load_lds_dwordx4 v[190:191], off
	s_add_i32 m0, s24, 0x2000
	s_add_u32 s24, s48, 0x40080
	v_lshl_add_u64 v[190:191], v[216:217], 0, s[60:61]
	s_addc_u32 s25, s49, 0
	s_add_i32 s48, s65, s21
	global_load_lds_dwordx4 v[190:191], off
	v_lshl_add_u64 v[190:191], s[24:25], 0, v[192:193]
	s_mov_b32 m0, s48
	s_nop 0
	global_load_lds_dwordx4 v[190:191], off
	v_lshl_add_u64 v[190:191], s[24:25], 0, v[128:129]
	s_add_i32 m0, s48, 0x2000
	s_nop 0
	global_load_lds_dwordx4 v[190:191], off
	v_lshl_add_u64 v[190:191], v[218:219], 0, s[60:61]
	s_mov_b32 m0, s29
	s_nop 0
	global_load_lds_dwordx4 v[190:191], off
	v_lshl_add_u64 v[190:191], v[220:221], 0, s[60:61]
	s_mov_b32 m0, s40
	s_nop 0
	global_load_lds_dwordx4 v[190:191], off
	s_waitcnt vmcnt(8) lgkmcnt(0)
	s_setprio 1
	s_barrier
	v_mfma_f32_16x16x32_bf16 v[60:63], v[138:141], v[174:177], v[60:63]
	v_mfma_f32_16x16x32_bf16 v[56:59], v[150:153], v[174:177], v[56:59]
	v_mfma_f32_16x16x32_bf16 v[44:47], v[138:141], v[182:185], v[44:47]
	v_mfma_f32_16x16x32_bf16 v[40:43], v[150:153], v[182:185], v[40:43]
	v_mfma_f32_16x16x32_bf16 v[28:31], v[138:141], v[200:203], v[28:31]
	v_mfma_f32_16x16x32_bf16 v[24:27], v[150:153], v[200:203], v[24:27]
	v_mfma_f32_16x16x32_bf16 v[12:15], v[138:141], v[208:211], v[12:15]
	v_mfma_f32_16x16x32_bf16 v[8:11], v[150:153], v[208:211], v[8:11]
	v_mfma_f32_16x16x32_bf16 v[60:63], v[146:149], v[178:181], v[60:63]
	v_mfma_f32_16x16x32_bf16 v[56:59], v[154:157], v[178:181], v[56:59]
	v_mfma_f32_16x16x32_bf16 v[44:47], v[146:149], v[186:189], v[44:47]
	v_mfma_f32_16x16x32_bf16 v[40:43], v[154:157], v[186:189], v[40:43]
	v_mfma_f32_16x16x32_bf16 v[28:31], v[146:149], v[204:207], v[28:31]
	v_mfma_f32_16x16x32_bf16 v[24:27], v[154:157], v[204:207], v[24:27]
	v_mfma_f32_16x16x32_bf16 v[12:15], v[146:149], v[212:215], v[12:15]
	v_mfma_f32_16x16x32_bf16 v[8:11], v[154:157], v[212:215], v[8:11]
	s_setprio 0
	s_setprio 1
	v_mfma_f32_16x16x32_bf16 v[52:55], v[158:161], v[174:177], v[52:55]
	v_mfma_f32_16x16x32_bf16 v[48:51], v[166:169], v[174:177], v[48:51]
	v_mfma_f32_16x16x32_bf16 v[36:39], v[158:161], v[182:185], v[36:39]
	v_mfma_f32_16x16x32_bf16 v[32:35], v[166:169], v[182:185], v[32:35]
	v_mfma_f32_16x16x32_bf16 v[20:23], v[158:161], v[200:203], v[20:23]
	v_mfma_f32_16x16x32_bf16 v[16:19], v[166:169], v[200:203], v[16:19]
	v_mfma_f32_16x16x32_bf16 v[4:7], v[158:161], v[208:211], v[4:7]
	v_mfma_f32_16x16x32_bf16 v[0:3], v[166:169], v[208:211], v[0:3]
	v_mfma_f32_16x16x32_bf16 v[52:55], v[162:165], v[178:181], v[52:55]
	v_mfma_f32_16x16x32_bf16 v[48:51], v[170:173], v[178:181], v[48:51]
	v_mfma_f32_16x16x32_bf16 v[36:39], v[162:165], v[186:189], v[36:39]
	v_mfma_f32_16x16x32_bf16 v[32:35], v[170:173], v[186:189], v[32:35]
	v_mfma_f32_16x16x32_bf16 v[20:23], v[162:165], v[204:207], v[20:23]
	v_mfma_f32_16x16x32_bf16 v[16:19], v[170:173], v[204:207], v[16:19]
	v_mfma_f32_16x16x32_bf16 v[4:7], v[162:165], v[212:215], v[4:7]
	v_mfma_f32_16x16x32_bf16 v[0:3], v[170:173], v[212:215], v[0:3]
	s_setprio 0
	s_barrier
	s_add_i32 s59, s59, 2
	s_add_u32 s55, s55, 0x100
	s_addc_u32 s58, s58, 0
	s_add_u32 s46, s46, 0x100
	s_addc_u32 s47, s47, 0
	s_cmp_gt_u32 s59, 13
	s_cbranch_scc0 .LBB0_36
	s_and_b64 vcc, exec, s[12:13]
	s_cbranch_vccz .LBB0_39
	s_barrier

; #define PG8_STAGE(bufoff, gbase, voff) do { _Pragma("unroll") for (int _i = 0; _i < 2; ++_i) \
;         __builtin_amdgcn_global_load_lds((const unsigned*)((const char*)(gbase) + (voff)[_i]), (PG8_LAS unsigned*)(lds + (bufoff) + ldsw + _i * 8192), 16, 0, 0); } while (0)
; #define PG8_LDA(dst, b, h) do { _Pragma("unroll") for (int m = 0; m < 4; ++m) _Pragma("unroll") for (int k = 0; k < 2; ++k) dst[m][k] = *(const PG8_LAS bf16x8*)(lds + PG8_SA(b, h) + aoff + m * 2048 + k * 1024); } while (0)
; #define PG8_LDB(dst, b, h) do { _Pragma("unroll") for (int n = 0; n < 2; ++n) _Pragma("unroll") for (int k = 0; k < 2; ++k) dst[n][k] = *(const PG8_LAS bf16x8*)(lds + PG8_SB(b, h) + boff + n * 2048 + k * 1024); } while (0)
; #define PG8_MMA(ai, bj, At, Bt) do { __builtin_amdgcn_s_setprio(1); _Pragma("unroll") for (int m = 0; m < 4; ++m) _Pragma("unroll") for (int n = 0; n < 2; ++n) _Pragma("unroll") for (int k = 0; k < 2; ++k) \
;         acc[ai][bj][m][n] = __builtin_amdgcn_mfma_f32_16x16x32_bf16(Bt[n][k], At[m][k], acc[ai][bj][m][n], 0, 0, 0); __builtin_amdgcn_s_setprio(0); } while (0)
; #define PG8_WAIT_V(n) asm volatile("s_waitcnt vmcnt(" #n ")" ::: "memory")
; #define PG8_WAIT_L(n) asm volatile("s_waitcnt lgkmcnt(" #n ")" ::: "memory")
; template <class Epi, class Sched, bool ALIGN_EPI = false, bool SP2 = false>
; __device__ __forceinline__ void gemm_phase(PG8_LAS unsigned char* lds, const Gemm g, const Sched& S, const Epi& E, const int tid) {
;     ...
;             const bool last = (t == nt - 2);
;             const char* a1 = cA + (size_t)(t + 1) * kstep;
;             const char* a2 = last ? nA : cA + (size_t)(t + 2) * kstep; const char* b2 = last ? nB : cB + (size_t)(t + 2) * kstep;
;             const char* a3 = a2 + kstep; const char* b3 = b2 + kstep;
;             if (last && has_next) S.a_ready(nxt);
;             if constexpr (SP2) {
;             PG8_LDB(B0, 0, 0); PG8_LDB(B1, 0, 1); PG8_SCHED; PG8_LDA(At, 0, 0); PG8_STAGE(PG8_SA(1, 1), a1 + hstepA, voffA);
;             PG8_WAIT_V(8); PG8_WAIT_L(0); PG8_BAR; PG8_MMA(0, 0, At, B0); PG8_MMA(0, 1, At, B1); PG8_BAR; PG8_SCHED;
;             PG8_LDA(At, 0, 1); PG8_STAGE(PG8_SB(0, 0), b2, voffB); PG8_STAGE(PG8_SB(0, 1), b2 + hstepB, voffB); PG8_STAGE(PG8_SA(0, 0), a2, voffA);
;             PG8_WAIT_V(8); PG8_WAIT_L(0); PG8_BAR; PG8_MMA(1, 0, At, B0); PG8_MMA(1, 1, At, B1); PG8_BAR; PG8_SCHED;
.LBB0_70:
	s_add_u32 s24, s50, 0xfffc0080
	s_addc_u32 s25, s51, -1
	s_add_i32 s68, 0, 0x10000
	s_cmp_eq_u32 s74, 12
	s_cselect_b32 s55, s19, s25
	s_cselect_b32 s54, s63, s24
	s_cselect_b32 s53, s13, s2
	s_cselect_b32 s52, s65, s78
	s_add_i32 s69, 0, 0x14000
	v_add_u32_e32 v140, s68, v155
	v_add_u32_e32 v166, s69, v155
	ds_read_b128 v[128:131], v140
	ds_read_b128 v[132:135], v140 offset:1024
	ds_read_b128 v[136:139], v140 offset:2048
	ds_read_b128 v[140:143], v140 offset:3072
	ds_read_b128 v[150:153], v166
	ds_read_b128 v[158:161], v166 offset:1024
	ds_read_b128 v[162:165], v166 offset:2048
	ds_read_b128 v[166:169], v166 offset:3072
	v_lshl_add_u64 v[190:191], s[50:51], 0, v[148:149]
	s_add_i32 m0, s21, 0xc000
	ds_read_b128 v[170:173], v157
	ds_read_b128 v[174:177], v157 offset:1024
	ds_read_b128 v[178:181], v157 offset:2048
	ds_read_b128 v[182:185], v157 offset:3072
	ds_read_b128 v[186:189], v157 offset:4096
	ds_read_b128 v[200:203], v157 offset:5120
	ds_read_b128 v[204:207], v157 offset:6144
	ds_read_b128 v[208:211], v157 offset:7168
	global_load_lds_dwordx4 v[190:191], off
	v_lshl_add_u64 v[190:191], s[50:51], 0, v[146:147]
	s_add_i32 m0, s21, 0xe000
	s_nop 0
	global_load_lds_dwordx4 v[190:191], off
	s_waitcnt vmcnt(8) lgkmcnt(0)
	s_setprio 1
	s_barrier
	v_mfma_f32_16x16x32_bf16 v[124:127], v[128:131], v[170:173], v[124:127]
	v_mfma_f32_16x16x32_bf16 v[120:123], v[136:139], v[170:173], v[120:123]
	v_mfma_f32_16x16x32_bf16 v[108:111], v[128:131], v[178:181], v[108:111]
	v_mfma_f32_16x16x32_bf16 v[104:107], v[136:139], v[178:181], v[104:107]
	v_mfma_f32_16x16x32_bf16 v[92:95], v[128:131], v[186:189], v[92:95]
	v_mfma_f32_16x16x32_bf16 v[88:91], v[136:139], v[186:189], v[88:91]
	v_mfma_f32_16x16x32_bf16 v[84:87], v[128:131], v[204:207], v[84:87]
	v_mfma_f32_16x16x32_bf16 v[80:83], v[136:139], v[204:207], v[80:83]
	v_mfma_f32_16x16x32_bf16 v[124:127], v[132:135], v[174:177], v[124:127]
	v_mfma_f32_16x16x32_bf16 v[120:123], v[140:143], v[174:177], v[120:123]
	v_mfma_f32_16x16x32_bf16 v[108:111], v[132:135], v[182:185], v[108:111]
	v_mfma_f32_16x16x32_bf16 v[104:107], v[140:143], v[182:185], v[104:107]
	v_mfma_f32_16x16x32_bf16 v[92:95], v[132:135], v[200:203], v[92:95]
	v_mfma_f32_16x16x32_bf16 v[88:91], v[140:143], v[200:203], v[88:91]
	v_mfma_f32_16x16x32_bf16 v[84:87], v[132:135], v[208:211], v[84:87]
	v_mfma_f32_16x16x32_bf16 v[80:83], v[140:143], v[208:211], v[80:83]
	s_setprio 0
	s_setprio 1
	v_mfma_f32_16x16x32_bf16 v[116:119], v[150:153], v[170:173], v[116:119]
	v_mfma_f32_16x16x32_bf16 v[112:115], v[162:165], v[170:173], v[112:115]
	v_mfma_f32_16x16x32_bf16 v[100:103], v[150:153], v[178:181], v[100:103]
	v_mfma_f32_16x16x32_bf16 v[96:99], v[162:165], v[178:181], v[96:99]
	v_mfma_f32_16x16x32_bf16 v[76:79], v[150:153], v[186:189], v[76:79]
	v_mfma_f32_16x16x32_bf16 v[72:75], v[162:165], v[186:189], v[72:75]
	v_mfma_f32_16x16x32_bf16 v[68:71], v[150:153], v[204:207], v[68:71]
	v_mfma_f32_16x16x32_bf16 v[64:67], v[162:165], v[204:207], v[64:67]
	v_mfma_f32_16x16x32_bf16 v[116:119], v[158:161], v[174:177], v[116:119]
	v_mfma_f32_16x16x32_bf16 v[112:115], v[166:169], v[174:177], v[112:115]
	v_mfma_f32_16x16x32_bf16 v[100:103], v[158:161], v[182:185], v[100:103]
	v_mfma_f32_16x16x32_bf16 v[96:99], v[166:169], v[182:185], v[96:99]
	v_mfma_f32_16x16x32_bf16 v[76:79], v[158:161], v[200:203], v[76:79]
	v_mfma_f32_16x16x32_bf16 v[72:75], v[166:169], v[200:203], v[72:75]
	v_mfma_f32_16x16x32_bf16 v[68:71], v[158:161], v[208:211], v[68:71]
	v_mfma_f32_16x16x32_bf16 v[64:67], v[166:169], v[208:211], v[64:67]
	s_setprio 0
	s_barrier
	s_add_i32 s24, s68, s20
	v_lshl_add_u64 v[190:191], s[52:53], 0, v[192:193]
	s_mov_b32 m0, s24
	ds_read_b128 v[170:173], v157 offset:16384
	ds_read_b128 v[174:177], v157 offset:17408
	ds_read_b128 v[178:181], v157 offset:18432
	ds_read_b128 v[182:185], v157 offset:19456
	ds_read_b128 v[186:189], v157 offset:20480
	ds_read_b128 v[200:203], v157 offset:21504
	ds_read_b128 v[204:207], v157 offset:22528
	ds_read_b128 v[208:211], v157 offset:23552
	global_load_lds_dwordx4 v[190:191], off
	s_add_i32 m0, s24, 0x2000
	s_add_u32 s24, s52, 0x40000
	v_lshl_add_u64 v[212:213], s[52:53], 0, v[144:145]
	s_addc_u32 s25, s53, 0
	s_add_i32 s68, s69, s20
	global_load_lds_dwordx4 v[212:213], off
	v_lshl_add_u64 v[214:215], s[24:25], 0, v[192:193]
	s_mov_b32 m0, s68
	v_lshl_add_u64 v[216:217], s[54:55], 0, v[144:145]
	global_load_lds_dwordx4 v[214:215], off
	v_lshl_add_u64 v[214:215], s[24:25], 0, v[144:145]
	s_add_i32 m0, s68, 0x2000
	s_nop 0
	global_load_lds_dwordx4 v[214:215], off
	v_lshl_add_u64 v[214:215], s[54:55], 0, v[192:193]
	s_mov_b32 m0, s21
	s_nop 0
	global_load_lds_dwordx4 v[214:215], off
	s_mov_b32 m0, s26
	s_nop 0
	global_load_lds_dwordx4 v[216:217], off
	s_waitcnt vmcnt(8) lgkmcnt(0)
	s_setprio 1
	s_barrier
; #define PG8_STAGE(bufoff, gbase, voff) do { _Pragma("unroll") for (int _i = 0; _i < 2; ++_i) \
;         __builtin_amdgcn_global_load_lds((const unsigned*)((const char*)(gbase) + (voff)[_i]), (PG8_LAS unsigned*)(lds + (bufoff) + ldsw + _i * 8192), 16, 0, 0); } while (0)
; #define PG8_LDA(dst, b, h) do { _Pragma("unroll") for (int m = 0; m < 4; ++m) _Pragma("unroll") for (int k = 0; k < 2; ++k) dst[m][k] = *(const PG8_LAS bf16x8*)(lds + PG8_SA(b, h) + aoff + m * 2048 + k * 1024); } while (0)
; #define PG8_LDB(dst, b, h) do { _Pragma("unroll") for (int n = 0; n < 2; ++n) _Pragma("unroll") for (int k = 0; k < 2; ++k) dst[n][k] = *(const PG8_LAS bf16x8*)(lds + PG8_SB(b, h) + boff + n * 2048 + k * 1024); } while (0)
; #define PG8_MMA(ai, bj, At, Bt) do { __builtin_amdgcn_s_setprio(1); _Pragma("unroll") for (int m = 0; m < 4; ++m) _Pragma("unroll") for (int n = 0; n < 2; ++n) _Pragma("unroll") for (int k = 0; k < 2; ++k) \
;         acc[ai][bj][m][n] = __builtin_amdgcn_mfma_f32_16x16x32_bf16(Bt[n][k], At[m][k], acc[ai][bj][m][n], 0, 0, 0); __builtin_amdgcn_s_setprio(0); } while (0)
; #define PG8_WAIT_V(n) asm volatile("s_waitcnt vmcnt(" #n ")" ::: "memory")
; #define PG8_WAIT_L(n) asm volatile("s_waitcnt lgkmcnt(" #n ")" ::: "memory")
; #define PG8_BAR __builtin_amdgcn_s_barrier()
; #define PG8_SCHED __builtin_amdgcn_sched_barrier(0)
; template <class Epi, class Sched, bool ALIGN_EPI = false, bool SP2 = false>
; __device__ __forceinline__ void gemm_phase(PG8_LAS unsigned char* lds, const Gemm g, const Sched& S, const Epi& E, const int tid) {
;     ...
;             PG8_WAIT_V(8); PG8_WAIT_L(0); PG8_BAR; PG8_MMA(1, 0, At, B0); PG8_MMA(1, 1, At, B1); PG8_BAR; PG8_SCHED;
;             PG8_LDB(B0, 1, 0); PG8_LDB(B1, 1, 1); PG8_SCHED; PG8_LDA(At, 1, 0); PG8_STAGE(PG8_SA(0, 1), a2 + hstepA, voffA);
;             PG8_WAIT_V(8); PG8_WAIT_L(0); PG8_BAR; PG8_MMA(0, 0, At, B0); PG8_MMA(0, 1, At, B1); PG8_BAR; PG8_SCHED;
	v_mfma_f32_16x16x32_bf16 v[60:63], v[128:131], v[170:173], v[60:63]
	v_mfma_f32_16x16x32_bf16 v[56:59], v[136:139], v[170:173], v[56:59]
	v_mfma_f32_16x16x32_bf16 v[52:55], v[128:131], v[178:181], v[52:55]
	v_mfma_f32_16x16x32_bf16 v[40:43], v[136:139], v[178:181], v[40:43]
	v_mfma_f32_16x16x32_bf16 v[28:31], v[128:131], v[186:189], v[28:31]
	v_mfma_f32_16x16x32_bf16 v[24:27], v[136:139], v[186:189], v[24:27]
	v_mfma_f32_16x16x32_bf16 v[16:19], v[128:131], v[204:207], v[16:19]
	v_mfma_f32_16x16x32_bf16 v[8:11], v[136:139], v[204:207], v[8:11]
	v_mfma_f32_16x16x32_bf16 v[60:63], v[132:135], v[174:177], v[60:63]
	v_mfma_f32_16x16x32_bf16 v[56:59], v[140:143], v[174:177], v[56:59]
	v_mfma_f32_16x16x32_bf16 v[52:55], v[132:135], v[182:185], v[52:55]
	v_mfma_f32_16x16x32_bf16 v[40:43], v[140:143], v[182:185], v[40:43]
	v_mfma_f32_16x16x32_bf16 v[28:31], v[132:135], v[200:203], v[28:31]
	v_mfma_f32_16x16x32_bf16 v[24:27], v[140:143], v[200:203], v[24:27]
	v_mfma_f32_16x16x32_bf16 v[16:19], v[132:135], v[208:211], v[16:19]
	v_mfma_f32_16x16x32_bf16 v[8:11], v[140:143], v[208:211], v[8:11]
	s_setprio 0
	s_setprio 1
	v_mfma_f32_16x16x32_bf16 v[48:51], v[150:153], v[170:173], v[48:51]
	v_mfma_f32_16x16x32_bf16 v[44:47], v[162:165], v[170:173], v[44:47]
	v_mfma_f32_16x16x32_bf16 v[36:39], v[150:153], v[178:181], v[36:39]
	v_mfma_f32_16x16x32_bf16 v[32:35], v[162:165], v[178:181], v[32:35]
	v_mfma_f32_16x16x32_bf16 v[20:23], v[150:153], v[186:189], v[20:23]
	v_mfma_f32_16x16x32_bf16 v[12:15], v[162:165], v[186:189], v[12:15]
	v_mfma_f32_16x16x32_bf16 v[4:7], v[150:153], v[204:207], v[4:7]
	v_mfma_f32_16x16x32_bf16 v[0:3], v[162:165], v[204:207], v[0:3]
	v_mfma_f32_16x16x32_bf16 v[48:51], v[158:161], v[174:177], v[48:51]
	v_mfma_f32_16x16x32_bf16 v[44:47], v[166:169], v[174:177], v[44:47]
	v_mfma_f32_16x16x32_bf16 v[36:39], v[158:161], v[182:185], v[36:39]
	v_mfma_f32_16x16x32_bf16 v[32:35], v[166:169], v[182:185], v[32:35]
	v_mfma_f32_16x16x32_bf16 v[20:23], v[158:161], v[200:203], v[20:23]
	v_mfma_f32_16x16x32_bf16 v[12:15], v[166:169], v[200:203], v[12:15]
	v_mfma_f32_16x16x32_bf16 v[4:7], v[158:161], v[208:211], v[4:7]
	v_mfma_f32_16x16x32_bf16 v[0:3], v[166:169], v[208:211], v[0:3]
	s_setprio 0
	s_barrier
	s_add_i32 s68, 0, 0x18000
	s_add_i32 s69, 0, 0x1c000
	v_add_u32_e32 v140, s68, v155
	v_add_u32_e32 v166, s69, v155
	ds_read_b128 v[128:131], v140
	ds_read_b128 v[132:135], v140 offset:1024
	ds_read_b128 v[136:139], v140 offset:2048
	ds_read_b128 v[140:143], v140 offset:3072
	ds_read_b128 v[150:153], v166
	ds_read_b128 v[158:161], v166 offset:1024
	ds_read_b128 v[162:165], v166 offset:2048
	ds_read_b128 v[166:169], v166 offset:3072
	s_add_u32 s24, s54, 0x40000
	s_addc_u32 s25, s55, 0
	s_mov_b32 m0, s27
	v_lshl_add_u64 v[218:219], s[24:25], 0, v[192:193]
	ds_read_b128 v[170:173], v157 offset:32768
	ds_read_b128 v[174:177], v157 offset:33792
	ds_read_b128 v[178:181], v157 offset:34816
	ds_read_b128 v[182:185], v157 offset:35840
	ds_read_b128 v[186:189], v157 offset:36864
	ds_read_b128 v[200:203], v157 offset:37888
	ds_read_b128 v[204:207], v157 offset:38912
	ds_read_b128 v[208:211], v157 offset:39936
	global_load_lds_dwordx4 v[218:219], off
	v_lshl_add_u64 v[218:219], s[24:25], 0, v[144:145]
	s_mov_b32 m0, s28
	s_nop 0
	global_load_lds_dwordx4 v[218:219], off
	s_waitcnt vmcnt(8) lgkmcnt(0)
	s_setprio 1
	s_barrier
	v_mfma_f32_16x16x32_bf16 v[124:127], v[128:131], v[170:173], v[124:127]
	v_mfma_f32_16x16x32_bf16 v[120:123], v[136:139], v[170:173], v[120:123]
	v_mfma_f32_16x16x32_bf16 v[108:111], v[128:131], v[178:181], v[108:111]
	v_mfma_f32_16x16x32_bf16 v[104:107], v[136:139], v[178:181], v[104:107]
	v_mfma_f32_16x16x32_bf16 v[92:95], v[128:131], v[186:189], v[92:95]
	v_mfma_f32_16x16x32_bf16 v[88:91], v[136:139], v[186:189], v[88:91]
	v_mfma_f32_16x16x32_bf16 v[84:87], v[128:131], v[204:207], v[84:87]
	v_mfma_f32_16x16x32_bf16 v[80:83], v[136:139], v[204:207], v[80:83]
	v_mfma_f32_16x16x32_bf16 v[124:127], v[132:135], v[174:177], v[124:127]
	v_mfma_f32_16x16x32_bf16 v[120:123], v[140:143], v[174:177], v[120:123]
	v_mfma_f32_16x16x32_bf16 v[108:111], v[132:135], v[182:185], v[108:111]
	v_mfma_f32_16x16x32_bf16 v[104:107], v[140:143], v[182:185], v[104:107]
	v_mfma_f32_16x16x32_bf16 v[92:95], v[132:135], v[200:203], v[92:95]
	v_mfma_f32_16x16x32_bf16 v[88:91], v[140:143], v[200:203], v[88:91]
	v_mfma_f32_16x16x32_bf16 v[84:87], v[132:135], v[208:211], v[84:87]
	v_mfma_f32_16x16x32_bf16 v[80:83], v[140:143], v[208:211], v[80:83]
	s_setprio 0
	s_setprio 1
	v_mfma_f32_16x16x32_bf16 v[116:119], v[150:153], v[170:173], v[116:119]
	v_mfma_f32_16x16x32_bf16 v[112:115], v[162:165], v[170:173], v[112:115]
	v_mfma_f32_16x16x32_bf16 v[100:103], v[150:153], v[178:181], v[100:103]
	v_mfma_f32_16x16x32_bf16 v[96:99], v[162:165], v[178:181], v[96:99]
	v_mfma_f32_16x16x32_bf16 v[76:79], v[150:153], v[186:189], v[76:79]
	v_mfma_f32_16x16x32_bf16 v[72:75], v[162:165], v[186:189], v[72:75]
	v_mfma_f32_16x16x32_bf16 v[68:71], v[150:153], v[204:207], v[68:71]
	v_mfma_f32_16x16x32_bf16 v[64:67], v[162:165], v[204:207], v[64:67]
	v_mfma_f32_16x16x32_bf16 v[116:119], v[158:161], v[174:177], v[116:119]
	v_mfma_f32_16x16x32_bf16 v[112:115], v[166:169], v[174:177], v[112:115]
	v_mfma_f32_16x16x32_bf16 v[100:103], v[158:161], v[182:185], v[100:103]
	v_mfma_f32_16x16x32_bf16 v[96:99], v[166:169], v[182:185], v[96:99]
	v_mfma_f32_16x16x32_bf16 v[76:79], v[158:161], v[200:203], v[76:79]
	v_mfma_f32_16x16x32_bf16 v[72:75], v[166:169], v[200:203], v[72:75]
	v_mfma_f32_16x16x32_bf16 v[68:71], v[158:161], v[208:211], v[68:71]
	v_mfma_f32_16x16x32_bf16 v[64:67], v[166:169], v[208:211], v[64:67]
	s_setprio 0
	s_barrier
; #define PG8_STAGE(bufoff, gbase, voff) do { _Pragma("unroll") for (int _i = 0; _i < 2; ++_i) \
;         __builtin_amdgcn_global_load_lds((const unsigned*)((const char*)(gbase) + (voff)[_i]), (PG8_LAS unsigned*)(lds + (bufoff) + ldsw + _i * 8192), 16, 0, 0); } while (0)
; #define PG8_LDA(dst, b, h) do { _Pragma("unroll") for (int m = 0; m < 4; ++m) _Pragma("unroll") for (int k = 0; k < 2; ++k) dst[m][k] = *(const PG8_LAS bf16x8*)(lds + PG8_SA(b, h) + aoff + m * 2048 + k * 1024); } while (0)
; #define PG8_MMA(ai, bj, At, Bt) do { __builtin_amdgcn_s_setprio(1); _Pragma("unroll") for (int m = 0; m < 4; ++m) _Pragma("unroll") for (int n = 0; n < 2; ++n) _Pragma("unroll") for (int k = 0; k < 2; ++k) \
;         acc[ai][bj][m][n] = __builtin_amdgcn_mfma_f32_16x16x32_bf16(Bt[n][k], At[m][k], acc[ai][bj][m][n], 0, 0, 0); __builtin_amdgcn_s_setprio(0); } while (0)
; #define PG8_WAIT_V(n) asm volatile("s_waitcnt vmcnt(" #n ")" ::: "memory")
; #define PG8_WAIT_L(n) asm volatile("s_waitcnt lgkmcnt(" #n ")" ::: "memory")
; #define PG8_BAR __builtin_amdgcn_s_barrier()
; #define PG8_SCHED __builtin_amdgcn_sched_barrier(0)
; template <class Epi, class Sched, bool ALIGN_EPI = false, bool SP2 = false>
; __device__ __forceinline__ void gemm_phase(PG8_LAS unsigned char* lds, const Gemm g, const Sched& S, const Epi& E, const int tid) {
;     ...
;             PG8_LDA(At, 1, 1); PG8_STAGE(PG8_SB(1, 0), b3, voffB); PG8_STAGE(PG8_SB(1, 1), b3 + hstepB, voffB); PG8_STAGE(PG8_SA(1, 0), a3, voffA);
;             PG8_WAIT_V(8); PG8_WAIT_L(0); PG8_BAR; PG8_MMA(1, 0, At, B0); PG8_MMA(1, 1, At, B1); PG8_BAR; PG8_SCHED;
;     ...
;         if constexpr (ALIGN_EPI) { if (wr == 0) PG8_BAR; }
	s_add_i32 s24, s68, s20
	v_lshl_add_u64 v[190:191], v[190:191], 0, s[60:61]
	s_mov_b32 m0, s24
	ds_read_b128 v[170:173], v157 offset:49152
	ds_read_b128 v[174:177], v157 offset:50176
	ds_read_b128 v[178:181], v157 offset:51200
	ds_read_b128 v[182:185], v157 offset:52224
	ds_read_b128 v[186:189], v157 offset:53248
	ds_read_b128 v[200:203], v157 offset:54272
	ds_read_b128 v[204:207], v157 offset:55296
	ds_read_b128 v[208:211], v157 offset:56320
	global_load_lds_dwordx4 v[190:191], off
	s_add_i32 m0, s24, 0x2000
	s_add_u32 s24, s52, 0x40080
	v_lshl_add_u64 v[190:191], v[212:213], 0, s[60:61]
	s_addc_u32 s25, s53, 0
	s_add_i32 s52, s69, s20
	global_load_lds_dwordx4 v[190:191], off
	v_lshl_add_u64 v[190:191], s[24:25], 0, v[192:193]
	s_mov_b32 m0, s52
	s_nop 0
	global_load_lds_dwordx4 v[190:191], off
	v_lshl_add_u64 v[190:191], s[24:25], 0, v[144:145]
	s_add_i32 m0, s52, 0x2000
	s_nop 0
	global_load_lds_dwordx4 v[190:191], off
	v_lshl_add_u64 v[190:191], v[214:215], 0, s[60:61]
	s_mov_b32 m0, s39
	s_nop 0
	global_load_lds_dwordx4 v[190:191], off
	v_lshl_add_u64 v[190:191], v[216:217], 0, s[60:61]
	s_mov_b32 m0, s40
	s_nop 0
	global_load_lds_dwordx4 v[190:191], off
	s_waitcnt vmcnt(8) lgkmcnt(0)
	s_setprio 1
	s_barrier
	v_mfma_f32_16x16x32_bf16 v[60:63], v[128:131], v[170:173], v[60:63]
	v_mfma_f32_16x16x32_bf16 v[56:59], v[136:139], v[170:173], v[56:59]
	v_mfma_f32_16x16x32_bf16 v[52:55], v[128:131], v[178:181], v[52:55]
	v_mfma_f32_16x16x32_bf16 v[40:43], v[136:139], v[178:181], v[40:43]
	v_mfma_f32_16x16x32_bf16 v[28:31], v[128:131], v[186:189], v[28:31]
	v_mfma_f32_16x16x32_bf16 v[24:27], v[136:139], v[186:189], v[24:27]
	v_mfma_f32_16x16x32_bf16 v[16:19], v[128:131], v[204:207], v[16:19]
	v_mfma_f32_16x16x32_bf16 v[8:11], v[136:139], v[204:207], v[8:11]
	v_mfma_f32_16x16x32_bf16 v[60:63], v[132:135], v[174:177], v[60:63]
	v_mfma_f32_16x16x32_bf16 v[56:59], v[140:143], v[174:177], v[56:59]
	v_mfma_f32_16x16x32_bf16 v[52:55], v[132:135], v[182:185], v[52:55]
	v_mfma_f32_16x16x32_bf16 v[40:43], v[140:143], v[182:185], v[40:43]
	v_mfma_f32_16x16x32_bf16 v[28:31], v[132:135], v[200:203], v[28:31]
	v_mfma_f32_16x16x32_bf16 v[24:27], v[140:143], v[200:203], v[24:27]
	v_mfma_f32_16x16x32_bf16 v[16:19], v[132:135], v[208:211], v[16:19]
	v_mfma_f32_16x16x32_bf16 v[8:11], v[140:143], v[208:211], v[8:11]
	s_setprio 0
	s_setprio 1
	v_mfma_f32_16x16x32_bf16 v[48:51], v[150:153], v[170:173], v[48:51]
	v_mfma_f32_16x16x32_bf16 v[44:47], v[162:165], v[170:173], v[44:47]
	v_mfma_f32_16x16x32_bf16 v[36:39], v[150:153], v[178:181], v[36:39]
	v_mfma_f32_16x16x32_bf16 v[32:35], v[162:165], v[178:181], v[32:35]
	v_mfma_f32_16x16x32_bf16 v[20:23], v[150:153], v[186:189], v[20:23]
	v_mfma_f32_16x16x32_bf16 v[12:15], v[162:165], v[186:189], v[12:15]
	v_mfma_f32_16x16x32_bf16 v[4:7], v[150:153], v[204:207], v[4:7]
	v_mfma_f32_16x16x32_bf16 v[0:3], v[162:165], v[204:207], v[0:3]
	v_mfma_f32_16x16x32_bf16 v[48:51], v[158:161], v[174:177], v[48:51]
	v_mfma_f32_16x16x32_bf16 v[44:47], v[166:169], v[174:177], v[44:47]
	v_mfma_f32_16x16x32_bf16 v[36:39], v[158:161], v[182:185], v[36:39]
	v_mfma_f32_16x16x32_bf16 v[32:35], v[166:169], v[182:185], v[32:35]
	v_mfma_f32_16x16x32_bf16 v[20:23], v[158:161], v[200:203], v[20:23]
	v_mfma_f32_16x16x32_bf16 v[12:15], v[166:169], v[200:203], v[12:15]
	v_mfma_f32_16x16x32_bf16 v[4:7], v[158:161], v[208:211], v[4:7]
	v_mfma_f32_16x16x32_bf16 v[0:3], v[166:169], v[208:211], v[0:3]
	s_setprio 0
	s_barrier
	s_add_i32 s74, s74, 2
	s_add_u32 s78, s78, 0x100
	s_addc_u32 s2, s2, 0
	s_add_u32 s50, s50, 0x100
	s_addc_u32 s51, s51, 0
	s_cmp_gt_u32 s74, 13
	s_cbranch_scc0 .LBB0_70
	s_and_b64 vcc, exec, s[10:11]
	s_cbranch_vccz .LBB0_73
	s_barrier

; #define PG8_STAGE(bufoff, gbase, voff) do { _Pragma("unroll") for (int _i = 0; _i < 2; ++_i) \
;         __builtin_amdgcn_global_load_lds((const unsigned*)((const char*)(gbase) + (voff)[_i]), (PG8_LAS unsigned*)(lds + (bufoff) + ldsw + _i * 8192), 16, 0, 0); } while (0)
; #define PG8_LDA(dst, b, h) do { _Pragma("unroll") for (int m = 0; m < 4; ++m) _Pragma("unroll") for (int k = 0; k < 2; ++k) dst[m][k] = *(const PG8_LAS bf16x8*)(lds + PG8_SA(b, h) + aoff + m * 2048 + k * 1024); } while (0)
; #define PG8_LDB(dst, b, h) do { _Pragma("unroll") for (int n = 0; n < 2; ++n) _Pragma("unroll") for (int k = 0; k < 2; ++k) dst[n][k] = *(const PG8_LAS bf16x8*)(lds + PG8_SB(b, h) + boff + n * 2048 + k * 1024); } while (0)
; #define PG8_MMA(ai, bj, At, Bt) do { __builtin_amdgcn_s_setprio(1); _Pragma("unroll") for (int m = 0; m < 4; ++m) _Pragma("unroll") for (int n = 0; n < 2; ++n) _Pragma("unroll") for (int k = 0; k < 2; ++k) \
;         acc[ai][bj][m][n] = __builtin_amdgcn_mfma_f32_16x16x32_bf16(Bt[n][k], At[m][k], acc[ai][bj][m][n], 0, 0, 0); __builtin_amdgcn_s_setprio(0); } while (0)
; #define PG8_WAIT_V(n) asm volatile("s_waitcnt vmcnt(" #n ")" ::: "memory")
; #define PG8_WAIT_L(n) asm volatile("s_waitcnt lgkmcnt(" #n ")" ::: "memory")
; template <class Epi, class Sched, bool ALIGN_EPI = false, bool SP2 = false>
; __device__ __forceinline__ void gemm_phase(PG8_LAS unsigned char* lds, const Gemm g, const Sched& S, const Epi& E, const int tid) {
;     ...
;             const bool last = (t == nt - 2);
;             const char* a1 = cA + (size_t)(t + 1) * kstep;
;             const char* a2 = last ? nA : cA + (size_t)(t + 2) * kstep; const char* b2 = last ? nB : cB + (size_t)(t + 2) * kstep;
;             const char* a3 = a2 + kstep; const char* b3 = b2 + kstep;
;             if (last && has_next) S.a_ready(nxt);
;             if constexpr (SP2) {
;             PG8_LDB(B0, 0, 0); PG8_LDB(B1, 0, 1); PG8_SCHED; PG8_LDA(At, 0, 0); PG8_STAGE(PG8_SA(1, 1), a1 + hstepA, voffA);
;             PG8_WAIT_V(8); PG8_WAIT_L(0); PG8_BAR; PG8_MMA(0, 0, At, B0); PG8_MMA(0, 1, At, B1); PG8_BAR; PG8_SCHED;
;             PG8_LDA(At, 0, 1); PG8_STAGE(PG8_SB(0, 0), b2, voffB); PG8_STAGE(PG8_SB(0, 1), b2 + hstepB, voffB); PG8_STAGE(PG8_SA(0, 0), a2, voffA);
;             PG8_WAIT_V(8); PG8_WAIT_L(0); PG8_BAR; PG8_MMA(1, 0, At, B0); PG8_MMA(1, 1, At, B1); PG8_BAR; PG8_SCHED;
.LBB0_90:
	s_add_u32 s25, s6, 0xfffe0080
	s_addc_u32 s68, s7, -1
	s_add_i32 s69, 0, 0x10000
	s_cmp_eq_u32 s24, 4
	s_cselect_b32 s89, s55, s68
	s_cselect_b32 s88, vcc_lo, s25
	s_cselect_b32 s87, s53, s74
	s_cselect_b32 s86, vcc_hi, s2
	s_add_i32 s25, 0, 0x14000
	v_add_u32_e32 v92, s69, v237
	v_add_u32_e32 v132, s25, v237
	ds_read_b128 v[64:67], v92
	ds_read_b128 v[76:79], v92 offset:1024
	ds_read_b128 v[80:83], v92 offset:2048
	ds_read_b128 v[92:95], v92 offset:3072
	ds_read_b128 v[104:107], v132
	ds_read_b128 v[116:119], v132 offset:1024
	ds_read_b128 v[128:131], v132 offset:2048
	ds_read_b128 v[132:135], v132 offset:3072
	v_lshl_add_u64 v[210:211], s[6:7], 0, v[208:209]
	s_add_i32 m0, s17, 0xc000
	ds_read_b128 v[160:163], v239
	ds_read_b128 v[164:167], v239 offset:1024
	ds_read_b128 v[168:171], v239 offset:2048
	ds_read_b128 v[172:175], v239 offset:3072
	ds_read_b128 v[176:179], v239 offset:4096
	ds_read_b128 v[180:183], v239 offset:5120
	ds_read_b128 v[184:187], v239 offset:6144
	ds_read_b128 v[188:191], v239 offset:7168
	global_load_lds_dwordx4 v[210:211], off
	v_lshl_add_u64 v[210:211], s[6:7], 0, v[206:207]
	s_add_i32 m0, s17, 0xe000
	s_nop 0
	global_load_lds_dwordx4 v[210:211], off
	s_waitcnt vmcnt(8) lgkmcnt(0)
	s_setprio 1
	s_barrier
	v_mfma_f32_16x16x32_bf16 v[156:159], v[64:67], v[160:163], v[156:159]
	v_mfma_f32_16x16x32_bf16 v[152:155], v[80:83], v[160:163], v[152:155]
	v_mfma_f32_16x16x32_bf16 v[140:143], v[64:67], v[168:171], v[140:143]
	v_mfma_f32_16x16x32_bf16 v[136:139], v[80:83], v[168:171], v[136:139]
	v_mfma_f32_16x16x32_bf16 v[112:115], v[64:67], v[176:179], v[112:115]
	v_mfma_f32_16x16x32_bf16 v[108:111], v[80:83], v[176:179], v[108:111]
	v_mfma_f32_16x16x32_bf16 v[88:91], v[64:67], v[184:187], v[88:91]
	v_mfma_f32_16x16x32_bf16 v[84:87], v[80:83], v[184:187], v[84:87]
	v_mfma_f32_16x16x32_bf16 v[156:159], v[76:79], v[164:167], v[156:159]
	v_mfma_f32_16x16x32_bf16 v[152:155], v[92:95], v[164:167], v[152:155]
	v_mfma_f32_16x16x32_bf16 v[140:143], v[76:79], v[172:175], v[140:143]
	v_mfma_f32_16x16x32_bf16 v[136:139], v[92:95], v[172:175], v[136:139]
	v_mfma_f32_16x16x32_bf16 v[112:115], v[76:79], v[180:183], v[112:115]
	v_mfma_f32_16x16x32_bf16 v[108:111], v[92:95], v[180:183], v[108:111]
	v_mfma_f32_16x16x32_bf16 v[88:91], v[76:79], v[188:191], v[88:91]
	v_mfma_f32_16x16x32_bf16 v[84:87], v[92:95], v[188:191], v[84:87]
	s_setprio 0
	s_setprio 1
	v_mfma_f32_16x16x32_bf16 v[148:151], v[104:107], v[160:163], v[148:151]
	v_mfma_f32_16x16x32_bf16 v[144:147], v[128:131], v[160:163], v[144:147]
	v_mfma_f32_16x16x32_bf16 v[124:127], v[104:107], v[168:171], v[124:127]
	v_mfma_f32_16x16x32_bf16 v[120:123], v[128:131], v[168:171], v[120:123]
	v_mfma_f32_16x16x32_bf16 v[100:103], v[104:107], v[176:179], v[100:103]
	v_mfma_f32_16x16x32_bf16 v[96:99], v[128:131], v[176:179], v[96:99]
	v_mfma_f32_16x16x32_bf16 v[72:75], v[104:107], v[184:187], v[72:75]
	v_mfma_f32_16x16x32_bf16 v[68:71], v[128:131], v[184:187], v[68:71]
	v_mfma_f32_16x16x32_bf16 v[148:151], v[116:119], v[164:167], v[148:151]
	v_mfma_f32_16x16x32_bf16 v[144:147], v[132:135], v[164:167], v[144:147]
	v_mfma_f32_16x16x32_bf16 v[124:127], v[116:119], v[172:175], v[124:127]
	v_mfma_f32_16x16x32_bf16 v[120:123], v[132:135], v[172:175], v[120:123]
	v_mfma_f32_16x16x32_bf16 v[100:103], v[116:119], v[180:183], v[100:103]
	v_mfma_f32_16x16x32_bf16 v[96:99], v[132:135], v[180:183], v[96:99]
	v_mfma_f32_16x16x32_bf16 v[72:75], v[116:119], v[188:191], v[72:75]
	v_mfma_f32_16x16x32_bf16 v[68:71], v[132:135], v[188:191], v[68:71]
	s_setprio 0
	s_barrier
	s_add_i32 s68, s69, s16
	v_lshl_add_u64 v[210:211], s[86:87], 0, v[192:193]
	s_mov_b32 m0, s68
	ds_read_b128 v[160:163], v239 offset:16384
	ds_read_b128 v[164:167], v239 offset:17408
	ds_read_b128 v[168:171], v239 offset:18432
	ds_read_b128 v[172:175], v239 offset:19456
	ds_read_b128 v[176:179], v239 offset:20480
	ds_read_b128 v[180:183], v239 offset:21504
	ds_read_b128 v[184:187], v239 offset:22528
	ds_read_b128 v[188:191], v239 offset:23552
	global_load_lds_dwordx4 v[210:211], off
	s_add_i32 m0, s68, 0x2000
	s_add_u32 s68, s86, 0x20000
	v_lshl_add_u64 v[212:213], s[86:87], 0, v[204:205]
	s_addc_u32 s69, s87, 0
	s_add_i32 s25, s25, s16
	global_load_lds_dwordx4 v[212:213], off
	v_lshl_add_u64 v[214:215], s[68:69], 0, v[192:193]
	s_mov_b32 m0, s25
	v_lshl_add_u64 v[216:217], s[88:89], 0, v[202:203]
	global_load_lds_dwordx4 v[214:215], off
	v_lshl_add_u64 v[214:215], s[68:69], 0, v[204:205]
	s_add_i32 m0, s25, 0x2000
	s_nop 0
	global_load_lds_dwordx4 v[214:215], off
	v_lshl_add_u64 v[214:215], s[88:89], 0, v[200:201]
	s_mov_b32 m0, s17
	s_nop 0
	global_load_lds_dwordx4 v[214:215], off
	s_mov_b32 m0, s38
	s_nop 0
	global_load_lds_dwordx4 v[216:217], off
	s_waitcnt vmcnt(8) lgkmcnt(0)
	s_setprio 1
	s_barrier
; #define PG8_STAGE(bufoff, gbase, voff) do { _Pragma("unroll") for (int _i = 0; _i < 2; ++_i) \
;         __builtin_amdgcn_global_load_lds((const unsigned*)((const char*)(gbase) + (voff)[_i]), (PG8_LAS unsigned*)(lds + (bufoff) + ldsw + _i * 8192), 16, 0, 0); } while (0)
; #define PG8_LDA(dst, b, h) do { _Pragma("unroll") for (int m = 0; m < 4; ++m) _Pragma("unroll") for (int k = 0; k < 2; ++k) dst[m][k] = *(const PG8_LAS bf16x8*)(lds + PG8_SA(b, h) + aoff + m * 2048 + k * 1024); } while (0)
; #define PG8_LDB(dst, b, h) do { _Pragma("unroll") for (int n = 0; n < 2; ++n) _Pragma("unroll") for (int k = 0; k < 2; ++k) dst[n][k] = *(const PG8_LAS bf16x8*)(lds + PG8_SB(b, h) + boff + n * 2048 + k * 1024); } while (0)
; #define PG8_MMA(ai, bj, At, Bt) do { __builtin_amdgcn_s_setprio(1); _Pragma("unroll") for (int m = 0; m < 4; ++m) _Pragma("unroll") for (int n = 0; n < 2; ++n) _Pragma("unroll") for (int k = 0; k < 2; ++k) \
;         acc[ai][bj][m][n] = __builtin_amdgcn_mfma_f32_16x16x32_bf16(Bt[n][k], At[m][k], acc[ai][bj][m][n], 0, 0, 0); __builtin_amdgcn_s_setprio(0); } while (0)
; #define PG8_WAIT_V(n) asm volatile("s_waitcnt vmcnt(" #n ")" ::: "memory")
; #define PG8_WAIT_L(n) asm volatile("s_waitcnt lgkmcnt(" #n ")" ::: "memory")
; #define PG8_BAR __builtin_amdgcn_s_barrier()
; #define PG8_SCHED __builtin_amdgcn_sched_barrier(0)
; template <class Epi, class Sched, bool ALIGN_EPI = false, bool SP2 = false>
; __device__ __forceinline__ void gemm_phase(PG8_LAS unsigned char* lds, const Gemm g, const Sched& S, const Epi& E, const int tid) {
;     ...
;             PG8_WAIT_V(8); PG8_WAIT_L(0); PG8_BAR; PG8_MMA(1, 0, At, B0); PG8_MMA(1, 1, At, B1); PG8_BAR; PG8_SCHED;
;             PG8_LDB(B0, 1, 0); PG8_LDB(B1, 1, 1); PG8_SCHED; PG8_LDA(At, 1, 0); PG8_STAGE(PG8_SA(0, 1), a2 + hstepA, voffA);
;             PG8_WAIT_V(8); PG8_WAIT_L(0); PG8_BAR; PG8_MMA(0, 0, At, B0); PG8_MMA(0, 1, At, B1); PG8_BAR; PG8_SCHED;
	v_mfma_f32_16x16x32_bf16 v[60:63], v[64:67], v[160:163], v[60:63]
	v_mfma_f32_16x16x32_bf16 v[56:59], v[80:83], v[160:163], v[56:59]
	v_mfma_f32_16x16x32_bf16 v[44:47], v[64:67], v[168:171], v[44:47]
	v_mfma_f32_16x16x32_bf16 v[40:43], v[80:83], v[168:171], v[40:43]
	v_mfma_f32_16x16x32_bf16 v[28:31], v[64:67], v[176:179], v[28:31]
	v_mfma_f32_16x16x32_bf16 v[24:27], v[80:83], v[176:179], v[24:27]
	v_mfma_f32_16x16x32_bf16 v[12:15], v[64:67], v[184:187], v[12:15]
	v_mfma_f32_16x16x32_bf16 v[8:11], v[80:83], v[184:187], v[8:11]
	v_mfma_f32_16x16x32_bf16 v[60:63], v[76:79], v[164:167], v[60:63]
	v_mfma_f32_16x16x32_bf16 v[56:59], v[92:95], v[164:167], v[56:59]
	v_mfma_f32_16x16x32_bf16 v[44:47], v[76:79], v[172:175], v[44:47]
	v_mfma_f32_16x16x32_bf16 v[40:43], v[92:95], v[172:175], v[40:43]
	v_mfma_f32_16x16x32_bf16 v[28:31], v[76:79], v[180:183], v[28:31]
	v_mfma_f32_16x16x32_bf16 v[24:27], v[92:95], v[180:183], v[24:27]
	v_mfma_f32_16x16x32_bf16 v[12:15], v[76:79], v[188:191], v[12:15]
	v_mfma_f32_16x16x32_bf16 v[8:11], v[92:95], v[188:191], v[8:11]
	s_setprio 0
	s_setprio 1
	v_mfma_f32_16x16x32_bf16 v[52:55], v[104:107], v[160:163], v[52:55]
	v_mfma_f32_16x16x32_bf16 v[48:51], v[128:131], v[160:163], v[48:51]
	v_mfma_f32_16x16x32_bf16 v[36:39], v[104:107], v[168:171], v[36:39]
	v_mfma_f32_16x16x32_bf16 v[32:35], v[128:131], v[168:171], v[32:35]
	v_mfma_f32_16x16x32_bf16 v[20:23], v[104:107], v[176:179], v[20:23]
	v_mfma_f32_16x16x32_bf16 v[16:19], v[128:131], v[176:179], v[16:19]
	v_mfma_f32_16x16x32_bf16 v[4:7], v[104:107], v[184:187], v[4:7]
	v_mfma_f32_16x16x32_bf16 v[0:3], v[128:131], v[184:187], v[0:3]
	v_mfma_f32_16x16x32_bf16 v[52:55], v[116:119], v[164:167], v[52:55]
	v_mfma_f32_16x16x32_bf16 v[48:51], v[132:135], v[164:167], v[48:51]
	v_mfma_f32_16x16x32_bf16 v[36:39], v[116:119], v[172:175], v[36:39]
	v_mfma_f32_16x16x32_bf16 v[32:35], v[132:135], v[172:175], v[32:35]
	v_mfma_f32_16x16x32_bf16 v[20:23], v[116:119], v[180:183], v[20:23]
	v_mfma_f32_16x16x32_bf16 v[16:19], v[132:135], v[180:183], v[16:19]
	v_mfma_f32_16x16x32_bf16 v[4:7], v[116:119], v[188:191], v[4:7]
	v_mfma_f32_16x16x32_bf16 v[0:3], v[132:135], v[188:191], v[0:3]
	s_setprio 0
	s_barrier
	s_add_i32 s25, 0, 0x18000
	s_add_i32 s56, 0, 0x1c000
	v_add_u32_e32 v92, s25, v237
	v_add_u32_e32 v132, s56, v237
	ds_read_b128 v[64:67], v92
	ds_read_b128 v[76:79], v92 offset:1024
	ds_read_b128 v[80:83], v92 offset:2048
	ds_read_b128 v[92:95], v92 offset:3072
	ds_read_b128 v[104:107], v132
	ds_read_b128 v[116:119], v132 offset:1024
	ds_read_b128 v[128:131], v132 offset:2048
	ds_read_b128 v[132:135], v132 offset:3072
	s_add_u32 s68, s88, 0x20000
	s_addc_u32 s69, s89, 0
	s_mov_b32 m0, s39
	v_lshl_add_u64 v[218:219], s[68:69], 0, v[200:201]
	ds_read_b128 v[160:163], v239 offset:32768
	ds_read_b128 v[164:167], v239 offset:33792
	ds_read_b128 v[168:171], v239 offset:34816
	ds_read_b128 v[172:175], v239 offset:35840
	ds_read_b128 v[176:179], v239 offset:36864
	ds_read_b128 v[180:183], v239 offset:37888
	ds_read_b128 v[184:187], v239 offset:38912
	ds_read_b128 v[188:191], v239 offset:39936
	global_load_lds_dwordx4 v[218:219], off
	v_lshl_add_u64 v[218:219], s[68:69], 0, v[202:203]
	s_mov_b32 m0, s28
	s_nop 0
	global_load_lds_dwordx4 v[218:219], off
	s_waitcnt vmcnt(8) lgkmcnt(0)
	s_setprio 1
	s_barrier
	v_mfma_f32_16x16x32_bf16 v[156:159], v[64:67], v[160:163], v[156:159]
	v_mfma_f32_16x16x32_bf16 v[152:155], v[80:83], v[160:163], v[152:155]
	v_mfma_f32_16x16x32_bf16 v[140:143], v[64:67], v[168:171], v[140:143]
	v_mfma_f32_16x16x32_bf16 v[136:139], v[80:83], v[168:171], v[136:139]
	v_mfma_f32_16x16x32_bf16 v[112:115], v[64:67], v[176:179], v[112:115]
	v_mfma_f32_16x16x32_bf16 v[108:111], v[80:83], v[176:179], v[108:111]
	v_mfma_f32_16x16x32_bf16 v[88:91], v[64:67], v[184:187], v[88:91]
	v_mfma_f32_16x16x32_bf16 v[84:87], v[80:83], v[184:187], v[84:87]
	v_mfma_f32_16x16x32_bf16 v[156:159], v[76:79], v[164:167], v[156:159]
	v_mfma_f32_16x16x32_bf16 v[152:155], v[92:95], v[164:167], v[152:155]
	v_mfma_f32_16x16x32_bf16 v[140:143], v[76:79], v[172:175], v[140:143]
	v_mfma_f32_16x16x32_bf16 v[136:139], v[92:95], v[172:175], v[136:139]
	v_mfma_f32_16x16x32_bf16 v[112:115], v[76:79], v[180:183], v[112:115]
	v_mfma_f32_16x16x32_bf16 v[108:111], v[92:95], v[180:183], v[108:111]
	v_mfma_f32_16x16x32_bf16 v[88:91], v[76:79], v[188:191], v[88:91]
	v_mfma_f32_16x16x32_bf16 v[84:87], v[92:95], v[188:191], v[84:87]
	s_setprio 0
	s_setprio 1
	v_mfma_f32_16x16x32_bf16 v[148:151], v[104:107], v[160:163], v[148:151]
	v_mfma_f32_16x16x32_bf16 v[144:147], v[128:131], v[160:163], v[144:147]
	v_mfma_f32_16x16x32_bf16 v[124:127], v[104:107], v[168:171], v[124:127]
	v_mfma_f32_16x16x32_bf16 v[120:123], v[128:131], v[168:171], v[120:123]
	v_mfma_f32_16x16x32_bf16 v[100:103], v[104:107], v[176:179], v[100:103]
	v_mfma_f32_16x16x32_bf16 v[96:99], v[128:131], v[176:179], v[96:99]
	v_mfma_f32_16x16x32_bf16 v[72:75], v[104:107], v[184:187], v[72:75]
	v_mfma_f32_16x16x32_bf16 v[68:71], v[128:131], v[184:187], v[68:71]
	v_mfma_f32_16x16x32_bf16 v[148:151], v[116:119], v[164:167], v[148:151]
	v_mfma_f32_16x16x32_bf16 v[144:147], v[132:135], v[164:167], v[144:147]
	v_mfma_f32_16x16x32_bf16 v[124:127], v[116:119], v[172:175], v[124:127]
	v_mfma_f32_16x16x32_bf16 v[120:123], v[132:135], v[172:175], v[120:123]
	v_mfma_f32_16x16x32_bf16 v[100:103], v[116:119], v[180:183], v[100:103]
	v_mfma_f32_16x16x32_bf16 v[96:99], v[132:135], v[180:183], v[96:99]
	v_mfma_f32_16x16x32_bf16 v[72:75], v[116:119], v[188:191], v[72:75]
	v_mfma_f32_16x16x32_bf16 v[68:71], v[132:135], v[188:191], v[68:71]
	s_setprio 0
	s_barrier
; #define PG8_STAGE(bufoff, gbase, voff) do { _Pragma("unroll") for (int _i = 0; _i < 2; ++_i) \
;         __builtin_amdgcn_global_load_lds((const unsigned*)((const char*)(gbase) + (voff)[_i]), (PG8_LAS unsigned*)(lds + (bufoff) + ldsw + _i * 8192), 16, 0, 0); } while (0)
; #define PG8_LDA(dst, b, h) do { _Pragma("unroll") for (int m = 0; m < 4; ++m) _Pragma("unroll") for (int k = 0; k < 2; ++k) dst[m][k] = *(const PG8_LAS bf16x8*)(lds + PG8_SA(b, h) + aoff + m * 2048 + k * 1024); } while (0)
; #define PG8_MMA(ai, bj, At, Bt) do { __builtin_amdgcn_s_setprio(1); _Pragma("unroll") for (int m = 0; m < 4; ++m) _Pragma("unroll") for (int n = 0; n < 2; ++n) _Pragma("unroll") for (int k = 0; k < 2; ++k) \
;         acc[ai][bj][m][n] = __builtin_amdgcn_mfma_f32_16x16x32_bf16(Bt[n][k], At[m][k], acc[ai][bj][m][n], 0, 0, 0); __builtin_amdgcn_s_setprio(0); } while (0)
; #define PG8_WAIT_V(n) asm volatile("s_waitcnt vmcnt(" #n ")" ::: "memory")
; #define PG8_WAIT_L(n) asm volatile("s_waitcnt lgkmcnt(" #n ")" ::: "memory")
; #define PG8_BAR __builtin_amdgcn_s_barrier()
; #define PG8_SCHED __builtin_amdgcn_sched_barrier(0)
; template <class Epi, class Sched, bool ALIGN_EPI = false, bool SP2 = false>
; __device__ __forceinline__ void gemm_phase(PG8_LAS unsigned char* lds, const Gemm g, const Sched& S, const Epi& E, const int tid) {
;     ...
;             PG8_LDA(At, 1, 1); PG8_STAGE(PG8_SB(1, 0), b3, voffB); PG8_STAGE(PG8_SB(1, 1), b3 + hstepB, voffB); PG8_STAGE(PG8_SA(1, 0), a3, voffA);
;             PG8_WAIT_V(8); PG8_WAIT_L(0); PG8_BAR; PG8_MMA(1, 0, At, B0); PG8_MMA(1, 1, At, B1); PG8_BAR; PG8_SCHED;
;     ...
;         if constexpr (ALIGN_EPI) { if (wr == 0) PG8_BAR; }
	s_add_i32 s25, s25, s16
	v_lshl_add_u64 v[210:211], v[210:211], 0, s[60:61]
	s_mov_b32 m0, s25
	ds_read_b128 v[160:163], v239 offset:49152
	ds_read_b128 v[164:167], v239 offset:50176
	ds_read_b128 v[168:171], v239 offset:51200
	ds_read_b128 v[172:175], v239 offset:52224
	ds_read_b128 v[176:179], v239 offset:53248
	ds_read_b128 v[180:183], v239 offset:54272
	ds_read_b128 v[184:187], v239 offset:55296
	ds_read_b128 v[188:191], v239 offset:56320
	global_load_lds_dwordx4 v[210:211], off
	s_add_i32 m0, s25, 0x2000
	s_add_u32 s68, s86, 0x20080
	v_lshl_add_u64 v[210:211], v[212:213], 0, s[60:61]
	s_addc_u32 s69, s87, 0
	s_add_i32 s25, s56, s16
	global_load_lds_dwordx4 v[210:211], off
	v_lshl_add_u64 v[210:211], s[68:69], 0, v[192:193]
	s_mov_b32 m0, s25
	s_nop 0
	global_load_lds_dwordx4 v[210:211], off
	v_lshl_add_u64 v[210:211], s[68:69], 0, v[204:205]
	s_add_i32 m0, s25, 0x2000
	s_nop 0
	global_load_lds_dwordx4 v[210:211], off
	v_lshl_add_u64 v[210:211], v[214:215], 0, s[60:61]
	s_mov_b32 m0, s29
	s_nop 0
	global_load_lds_dwordx4 v[210:211], off
	v_lshl_add_u64 v[210:211], v[216:217], 0, s[60:61]
	s_mov_b32 m0, s14
	s_nop 0
	global_load_lds_dwordx4 v[210:211], off
	s_waitcnt vmcnt(8) lgkmcnt(0)
	s_setprio 1
	s_barrier
	v_mfma_f32_16x16x32_bf16 v[60:63], v[64:67], v[160:163], v[60:63]
	v_mfma_f32_16x16x32_bf16 v[56:59], v[80:83], v[160:163], v[56:59]
	v_mfma_f32_16x16x32_bf16 v[44:47], v[64:67], v[168:171], v[44:47]
	v_mfma_f32_16x16x32_bf16 v[40:43], v[80:83], v[168:171], v[40:43]
	v_mfma_f32_16x16x32_bf16 v[28:31], v[64:67], v[176:179], v[28:31]
	v_mfma_f32_16x16x32_bf16 v[24:27], v[80:83], v[176:179], v[24:27]
	v_mfma_f32_16x16x32_bf16 v[12:15], v[64:67], v[184:187], v[12:15]
	v_mfma_f32_16x16x32_bf16 v[8:11], v[80:83], v[184:187], v[8:11]
	v_mfma_f32_16x16x32_bf16 v[60:63], v[76:79], v[164:167], v[60:63]
	v_mfma_f32_16x16x32_bf16 v[56:59], v[92:95], v[164:167], v[56:59]
	v_mfma_f32_16x16x32_bf16 v[44:47], v[76:79], v[172:175], v[44:47]
	v_mfma_f32_16x16x32_bf16 v[40:43], v[92:95], v[172:175], v[40:43]
	v_mfma_f32_16x16x32_bf16 v[28:31], v[76:79], v[180:183], v[28:31]
	v_mfma_f32_16x16x32_bf16 v[24:27], v[92:95], v[180:183], v[24:27]
	v_mfma_f32_16x16x32_bf16 v[12:15], v[76:79], v[188:191], v[12:15]
	v_mfma_f32_16x16x32_bf16 v[8:11], v[92:95], v[188:191], v[8:11]
	s_setprio 0
	s_setprio 1
	v_mfma_f32_16x16x32_bf16 v[52:55], v[104:107], v[160:163], v[52:55]
	v_mfma_f32_16x16x32_bf16 v[48:51], v[128:131], v[160:163], v[48:51]
	v_mfma_f32_16x16x32_bf16 v[36:39], v[104:107], v[168:171], v[36:39]
	v_mfma_f32_16x16x32_bf16 v[32:35], v[128:131], v[168:171], v[32:35]
	v_mfma_f32_16x16x32_bf16 v[20:23], v[104:107], v[176:179], v[20:23]
	v_mfma_f32_16x16x32_bf16 v[16:19], v[128:131], v[176:179], v[16:19]
	v_mfma_f32_16x16x32_bf16 v[4:7], v[104:107], v[184:187], v[4:7]
	v_mfma_f32_16x16x32_bf16 v[0:3], v[128:131], v[184:187], v[0:3]
	v_mfma_f32_16x16x32_bf16 v[52:55], v[116:119], v[164:167], v[52:55]
	v_mfma_f32_16x16x32_bf16 v[48:51], v[132:135], v[164:167], v[48:51]
	v_mfma_f32_16x16x32_bf16 v[36:39], v[116:119], v[172:175], v[36:39]
	v_mfma_f32_16x16x32_bf16 v[32:35], v[132:135], v[172:175], v[32:35]
	v_mfma_f32_16x16x32_bf16 v[20:23], v[116:119], v[180:183], v[20:23]
	v_mfma_f32_16x16x32_bf16 v[16:19], v[132:135], v[180:183], v[16:19]
	v_mfma_f32_16x16x32_bf16 v[4:7], v[116:119], v[188:191], v[4:7]
	v_mfma_f32_16x16x32_bf16 v[0:3], v[132:135], v[188:191], v[0:3]
	s_setprio 0
	s_barrier
	s_add_i32 s24, s24, 2
	s_add_u32 s2, s2, 0x100
	s_addc_u32 s74, s74, 0
	s_add_u32 s6, s6, 0x100
	s_addc_u32 s7, s7, 0
	s_cmp_gt_u32 s24, 5
	s_cbranch_scc0 .LBB0_90
	s_and_b64 vcc, exec, s[48:49]
	s_cbranch_vccz .LBB0_93
	s_barrier

; #define PG8_STAGE(bufoff, gbase, voff) do { _Pragma("unroll") for (int _i = 0; _i < 2; ++_i) \
;         __builtin_amdgcn_global_load_lds((const unsigned*)((const char*)(gbase) + (voff)[_i]), (PG8_LAS unsigned*)(lds + (bufoff) + ldsw + _i * 8192), 16, 0, 0); } while (0)
; #define PG8_LDA(dst, b, h) do { _Pragma("unroll") for (int m = 0; m < 4; ++m) _Pragma("unroll") for (int k = 0; k < 2; ++k) dst[m][k] = *(const PG8_LAS bf16x8*)(lds + PG8_SA(b, h) + aoff + m * 2048 + k * 1024); } while (0)
; #define PG8_LDB(dst, b, h) do { _Pragma("unroll") for (int n = 0; n < 2; ++n) _Pragma("unroll") for (int k = 0; k < 2; ++k) dst[n][k] = *(const PG8_LAS bf16x8*)(lds + PG8_SB(b, h) + boff + n * 2048 + k * 1024); } while (0)
; #define PG8_MMA(ai, bj, At, Bt) do { __builtin_amdgcn_s_setprio(1); _Pragma("unroll") for (int m = 0; m < 4; ++m) _Pragma("unroll") for (int n = 0; n < 2; ++n) _Pragma("unroll") for (int k = 0; k < 2; ++k) \
;         acc[ai][bj][m][n] = __builtin_amdgcn_mfma_f32_16x16x32_bf16(Bt[n][k], At[m][k], acc[ai][bj][m][n], 0, 0, 0); __builtin_amdgcn_s_setprio(0); } while (0)
; #define PG8_WAIT_V(n) asm volatile("s_waitcnt vmcnt(" #n ")" ::: "memory")
; #define PG8_WAIT_L(n) asm volatile("s_waitcnt lgkmcnt(" #n ")" ::: "memory")
; template <class Epi, class Sched, bool ALIGN_EPI = false, bool SP2 = false>
; __device__ __forceinline__ void gemm_phase(PG8_LAS unsigned char* lds, const Gemm g, const Sched& S, const Epi& E, const int tid) {
;     ...
;             const bool last = (t == nt - 2);
;             const char* a1 = cA + (size_t)(t + 1) * kstep;
;             const char* a2 = last ? nA : cA + (size_t)(t + 2) * kstep; const char* b2 = last ? nB : cB + (size_t)(t + 2) * kstep;
;             const char* a3 = a2 + kstep; const char* b3 = b2 + kstep;
;             if (last && has_next) S.a_ready(nxt);
;             if constexpr (SP2) {
;             PG8_LDB(B0, 0, 0); PG8_LDB(B1, 0, 1); PG8_SCHED; PG8_LDA(At, 0, 0); PG8_STAGE(PG8_SA(1, 1), a1 + hstepA, voffA);
;             PG8_WAIT_V(8); PG8_WAIT_L(0); PG8_BAR; PG8_MMA(0, 0, At, B0); PG8_MMA(0, 1, At, B1); PG8_BAR; PG8_SCHED;
;             PG8_LDA(At, 0, 1); PG8_STAGE(PG8_SB(0, 0), b2, voffB); PG8_STAGE(PG8_SB(0, 1), b2 + hstepB, voffB); PG8_STAGE(PG8_SA(0, 0), a2, voffA);
;             PG8_WAIT_V(8); PG8_WAIT_L(0); PG8_BAR; PG8_MMA(1, 0, At, B0); PG8_MMA(1, 1, At, B1); PG8_BAR; PG8_SCHED;
.LBB0_248:
	s_add_i32 vcc_lo, s52, 2
	s_add_u32 s50, s48, 0x100
	s_addc_u32 s51, s49, 0
	s_add_i32 s68, 0, 0x10000
	s_cmp_eq_u32 s87, s52
	s_cselect_b32 s53, s45, s51
	s_cselect_b32 s52, s44, s50
	v_add_u32_e32 v142, s68, v155
	s_cselect_b32 s43, s47, s25
	s_cselect_b32 s42, s46, s24
	s_add_i32 s69, 0, 0x14000
	ds_read_b128 v[138:141], v142
	ds_read_b128 v[158:161], v142 offset:1024
	ds_read_b128 v[162:165], v142 offset:2048
	ds_read_b128 v[166:169], v142 offset:3072
	v_add_u32_e32 v142, s69, v155
	ds_read_b128 v[170:173], v142
	ds_read_b128 v[174:177], v142 offset:1024
	ds_read_b128 v[178:181], v142 offset:2048
	ds_read_b128 v[182:185], v142 offset:3072
	v_lshl_add_u64 v[142:143], s[48:49], 0, v[134:135]
	s_add_i32 m0, s79, 0xc000
	ds_read_b128 v[186:189], v157
	ds_read_b128 v[200:203], v157 offset:1024
	ds_read_b128 v[204:207], v157 offset:2048
	ds_read_b128 v[208:211], v157 offset:3072
	ds_read_b128 v[212:215], v157 offset:4096
	ds_read_b128 v[216:219], v157 offset:5120
	ds_read_b128 v[220:223], v157 offset:6144
	ds_read_b128 v[234:237], v157 offset:7168
	global_load_lds_dwordx4 v[142:143], off
	v_lshl_add_u64 v[142:143], s[48:49], 0, v[132:133]
	s_add_i32 m0, s79, 0xe000
	s_nop 0
	global_load_lds_dwordx4 v[142:143], off
	s_waitcnt vmcnt(8) lgkmcnt(0)
	s_setprio 1
	s_barrier
	v_mfma_f32_16x16x32_bf16 v[124:127], v[138:141], v[186:189], v[124:127]
	v_mfma_f32_16x16x32_bf16 v[120:123], v[162:165], v[186:189], v[120:123]
	v_mfma_f32_16x16x32_bf16 v[108:111], v[138:141], v[204:207], v[108:111]
	v_mfma_f32_16x16x32_bf16 v[104:107], v[162:165], v[204:207], v[104:107]
	v_mfma_f32_16x16x32_bf16 v[92:95], v[138:141], v[212:215], v[92:95]
	v_mfma_f32_16x16x32_bf16 v[88:91], v[162:165], v[212:215], v[88:91]
	v_mfma_f32_16x16x32_bf16 v[76:79], v[138:141], v[220:223], v[76:79]
	v_mfma_f32_16x16x32_bf16 v[72:75], v[162:165], v[220:223], v[72:75]
	v_mfma_f32_16x16x32_bf16 v[124:127], v[158:161], v[200:203], v[124:127]
	v_mfma_f32_16x16x32_bf16 v[120:123], v[166:169], v[200:203], v[120:123]
	v_mfma_f32_16x16x32_bf16 v[108:111], v[158:161], v[208:211], v[108:111]
	v_mfma_f32_16x16x32_bf16 v[104:107], v[166:169], v[208:211], v[104:107]
	v_mfma_f32_16x16x32_bf16 v[92:95], v[158:161], v[216:219], v[92:95]
	v_mfma_f32_16x16x32_bf16 v[88:91], v[166:169], v[216:219], v[88:91]
	v_mfma_f32_16x16x32_bf16 v[76:79], v[158:161], v[234:237], v[76:79]
	v_mfma_f32_16x16x32_bf16 v[72:75], v[166:169], v[234:237], v[72:75]
	s_setprio 0
	s_setprio 1
	v_mfma_f32_16x16x32_bf16 v[116:119], v[170:173], v[186:189], v[116:119]
	v_mfma_f32_16x16x32_bf16 v[112:115], v[178:181], v[186:189], v[112:115]
	v_mfma_f32_16x16x32_bf16 v[100:103], v[170:173], v[204:207], v[100:103]
	v_mfma_f32_16x16x32_bf16 v[96:99], v[178:181], v[204:207], v[96:99]
	v_mfma_f32_16x16x32_bf16 v[84:87], v[170:173], v[212:215], v[84:87]
	v_mfma_f32_16x16x32_bf16 v[80:83], v[178:181], v[212:215], v[80:83]
	v_mfma_f32_16x16x32_bf16 v[68:71], v[170:173], v[220:223], v[68:71]
	v_mfma_f32_16x16x32_bf16 v[64:67], v[178:181], v[220:223], v[64:67]
	v_mfma_f32_16x16x32_bf16 v[116:119], v[174:177], v[200:203], v[116:119]
	v_mfma_f32_16x16x32_bf16 v[112:115], v[182:185], v[200:203], v[112:115]
	v_mfma_f32_16x16x32_bf16 v[100:103], v[174:177], v[208:211], v[100:103]
	v_mfma_f32_16x16x32_bf16 v[96:99], v[182:185], v[208:211], v[96:99]
	v_mfma_f32_16x16x32_bf16 v[84:87], v[174:177], v[216:219], v[84:87]
	v_mfma_f32_16x16x32_bf16 v[80:83], v[182:185], v[216:219], v[80:83]
	v_mfma_f32_16x16x32_bf16 v[68:71], v[174:177], v[234:237], v[68:71]
	v_mfma_f32_16x16x32_bf16 v[64:67], v[182:185], v[234:237], v[64:67]
	s_setprio 0
	s_barrier
	s_add_i32 s48, s68, s65
	v_lshl_add_u64 v[142:143], s[42:43], 0, v[192:193]
	s_mov_b32 m0, s48
	ds_read_b128 v[186:189], v157 offset:16384
	ds_read_b128 v[200:203], v157 offset:17408
	ds_read_b128 v[204:207], v157 offset:18432
	ds_read_b128 v[208:211], v157 offset:19456
	ds_read_b128 v[212:215], v157 offset:20480
	ds_read_b128 v[216:219], v157 offset:21504
	ds_read_b128 v[220:223], v157 offset:22528
	ds_read_b128 v[234:237], v157 offset:23552
	global_load_lds_dwordx4 v[142:143], off
	s_add_i32 m0, s48, 0x2000
	v_lshl_add_u64 v[190:191], s[42:43], 0, v[136:137]
	s_add_u32 s42, s42, s55
	s_addc_u32 s43, s43, 0
	s_add_i32 s48, s69, s65
	global_load_lds_dwordx4 v[190:191], off
	v_lshl_add_u64 v[238:239], s[42:43], 0, v[192:193]
	s_mov_b32 m0, s48
	v_lshl_add_u64 v[240:241], s[42:43], 0, v[136:137]
	global_load_lds_dwordx4 v[238:239], off
	s_add_i32 m0, s48, 0x2000
	v_lshl_add_u64 v[242:243], s[52:53], 0, v[130:131]
	global_load_lds_dwordx4 v[240:241], off
	s_mov_b32 m0, s79
	v_lshl_add_u64 v[244:245], s[52:53], 0, v[128:129]
	global_load_lds_dwordx4 v[242:243], off
	s_mov_b32 m0, s80
	s_nop 0
	global_load_lds_dwordx4 v[244:245], off
	s_waitcnt vmcnt(8) lgkmcnt(0)
	s_setprio 1
	s_barrier
; #define PG8_STAGE(bufoff, gbase, voff) do { _Pragma("unroll") for (int _i = 0; _i < 2; ++_i) \
;         __builtin_amdgcn_global_load_lds((const unsigned*)((const char*)(gbase) + (voff)[_i]), (PG8_LAS unsigned*)(lds + (bufoff) + ldsw + _i * 8192), 16, 0, 0); } while (0)
; #define PG8_LDA(dst, b, h) do { _Pragma("unroll") for (int m = 0; m < 4; ++m) _Pragma("unroll") for (int k = 0; k < 2; ++k) dst[m][k] = *(const PG8_LAS bf16x8*)(lds + PG8_SA(b, h) + aoff + m * 2048 + k * 1024); } while (0)
; #define PG8_LDB(dst, b, h) do { _Pragma("unroll") for (int n = 0; n < 2; ++n) _Pragma("unroll") for (int k = 0; k < 2; ++k) dst[n][k] = *(const PG8_LAS bf16x8*)(lds + PG8_SB(b, h) + boff + n * 2048 + k * 1024); } while (0)
; #define PG8_MMA(ai, bj, At, Bt) do { __builtin_amdgcn_s_setprio(1); _Pragma("unroll") for (int m = 0; m < 4; ++m) _Pragma("unroll") for (int n = 0; n < 2; ++n) _Pragma("unroll") for (int k = 0; k < 2; ++k) \
;         acc[ai][bj][m][n] = __builtin_amdgcn_mfma_f32_16x16x32_bf16(Bt[n][k], At[m][k], acc[ai][bj][m][n], 0, 0, 0); __builtin_amdgcn_s_setprio(0); } while (0)
; #define PG8_WAIT_V(n) asm volatile("s_waitcnt vmcnt(" #n ")" ::: "memory")
; #define PG8_WAIT_L(n) asm volatile("s_waitcnt lgkmcnt(" #n ")" ::: "memory")
; #define PG8_BAR __builtin_amdgcn_s_barrier()
; #define PG8_SCHED __builtin_amdgcn_sched_barrier(0)
; template <class Epi, class Sched, bool ALIGN_EPI = false, bool SP2 = false>
; __device__ __forceinline__ void gemm_phase(PG8_LAS unsigned char* lds, const Gemm g, const Sched& S, const Epi& E, const int tid) {
;     ...
;             PG8_WAIT_V(8); PG8_WAIT_L(0); PG8_BAR; PG8_MMA(1, 0, At, B0); PG8_MMA(1, 1, At, B1); PG8_BAR; PG8_SCHED;
;             PG8_LDB(B0, 1, 0); PG8_LDB(B1, 1, 1); PG8_SCHED; PG8_LDA(At, 1, 0); PG8_STAGE(PG8_SA(0, 1), a2 + hstepA, voffA);
;             PG8_WAIT_V(8); PG8_WAIT_L(0); PG8_BAR; PG8_MMA(0, 0, At, B0); PG8_MMA(0, 1, At, B1); PG8_BAR; PG8_SCHED;
	v_mfma_f32_16x16x32_bf16 v[60:63], v[138:141], v[186:189], v[60:63]
	v_mfma_f32_16x16x32_bf16 v[56:59], v[162:165], v[186:189], v[56:59]
	v_mfma_f32_16x16x32_bf16 v[44:47], v[138:141], v[204:207], v[44:47]
	v_mfma_f32_16x16x32_bf16 v[40:43], v[162:165], v[204:207], v[40:43]
	v_mfma_f32_16x16x32_bf16 v[28:31], v[138:141], v[212:215], v[28:31]
	v_mfma_f32_16x16x32_bf16 v[24:27], v[162:165], v[212:215], v[24:27]
	v_mfma_f32_16x16x32_bf16 v[12:15], v[138:141], v[220:223], v[12:15]
	v_mfma_f32_16x16x32_bf16 v[8:11], v[162:165], v[220:223], v[8:11]
	v_mfma_f32_16x16x32_bf16 v[60:63], v[158:161], v[200:203], v[60:63]
	v_mfma_f32_16x16x32_bf16 v[56:59], v[166:169], v[200:203], v[56:59]
	v_mfma_f32_16x16x32_bf16 v[44:47], v[158:161], v[208:211], v[44:47]
	v_mfma_f32_16x16x32_bf16 v[40:43], v[166:169], v[208:211], v[40:43]
	v_mfma_f32_16x16x32_bf16 v[28:31], v[158:161], v[216:219], v[28:31]
	v_mfma_f32_16x16x32_bf16 v[24:27], v[166:169], v[216:219], v[24:27]
	v_mfma_f32_16x16x32_bf16 v[12:15], v[158:161], v[234:237], v[12:15]
	v_mfma_f32_16x16x32_bf16 v[8:11], v[166:169], v[234:237], v[8:11]
	s_setprio 0
	s_setprio 1
	v_mfma_f32_16x16x32_bf16 v[52:55], v[170:173], v[186:189], v[52:55]
	v_mfma_f32_16x16x32_bf16 v[48:51], v[178:181], v[186:189], v[48:51]
	v_mfma_f32_16x16x32_bf16 v[36:39], v[170:173], v[204:207], v[36:39]
	v_mfma_f32_16x16x32_bf16 v[32:35], v[178:181], v[204:207], v[32:35]
	v_mfma_f32_16x16x32_bf16 v[20:23], v[170:173], v[212:215], v[20:23]
	v_mfma_f32_16x16x32_bf16 v[16:19], v[178:181], v[212:215], v[16:19]
	v_mfma_f32_16x16x32_bf16 v[4:7], v[170:173], v[220:223], v[4:7]
	v_mfma_f32_16x16x32_bf16 v[0:3], v[178:181], v[220:223], v[0:3]
	v_mfma_f32_16x16x32_bf16 v[52:55], v[174:177], v[200:203], v[52:55]
	v_mfma_f32_16x16x32_bf16 v[48:51], v[182:185], v[200:203], v[48:51]
	v_mfma_f32_16x16x32_bf16 v[36:39], v[174:177], v[208:211], v[36:39]
	v_mfma_f32_16x16x32_bf16 v[32:35], v[182:185], v[208:211], v[32:35]
	v_mfma_f32_16x16x32_bf16 v[20:23], v[174:177], v[216:219], v[20:23]
	v_mfma_f32_16x16x32_bf16 v[16:19], v[182:185], v[216:219], v[16:19]
	v_mfma_f32_16x16x32_bf16 v[4:7], v[174:177], v[234:237], v[4:7]
	v_mfma_f32_16x16x32_bf16 v[0:3], v[182:185], v[234:237], v[0:3]
	s_setprio 0
	s_barrier
	s_add_i32 s48, 0, 0x18000
	v_add_u32_e32 v144, s48, v155
	s_add_i32 s49, 0, 0x1c000
	ds_read_b128 v[138:141], v144
	ds_read_b128 v[158:161], v144 offset:1024
	ds_read_b128 v[162:165], v144 offset:2048
	ds_read_b128 v[166:169], v144 offset:3072
	v_add_u32_e32 v144, s49, v155
	ds_read_b128 v[170:173], v144
	ds_read_b128 v[174:177], v144 offset:1024
	ds_read_b128 v[178:181], v144 offset:2048
	ds_read_b128 v[182:185], v144 offset:3072
	s_add_u32 s42, s52, 0x30000
	s_addc_u32 s43, s53, 0
	s_mov_b32 m0, s81
	v_lshl_add_u64 v[246:247], s[42:43], 0, v[130:131]
	ds_read_b128 v[186:189], v157 offset:32768
	ds_read_b128 v[200:203], v157 offset:33792
	ds_read_b128 v[204:207], v157 offset:34816
	ds_read_b128 v[208:211], v157 offset:35840
	ds_read_b128 v[212:215], v157 offset:36864
	ds_read_b128 v[216:219], v157 offset:37888
	ds_read_b128 v[220:223], v157 offset:38912
	ds_read_b128 v[234:237], v157 offset:39936
	global_load_lds_dwordx4 v[246:247], off
	v_lshl_add_u64 v[246:247], s[42:43], 0, v[128:129]
	s_mov_b32 m0, s82
	s_nop 0
	global_load_lds_dwordx4 v[246:247], off
	s_waitcnt vmcnt(8) lgkmcnt(0)
	s_setprio 1
	s_barrier
	v_mfma_f32_16x16x32_bf16 v[124:127], v[138:141], v[186:189], v[124:127]
	v_mfma_f32_16x16x32_bf16 v[120:123], v[162:165], v[186:189], v[120:123]
	v_mfma_f32_16x16x32_bf16 v[108:111], v[138:141], v[204:207], v[108:111]
	v_mfma_f32_16x16x32_bf16 v[104:107], v[162:165], v[204:207], v[104:107]
	v_mfma_f32_16x16x32_bf16 v[92:95], v[138:141], v[212:215], v[92:95]
	v_mfma_f32_16x16x32_bf16 v[88:91], v[162:165], v[212:215], v[88:91]
	v_mfma_f32_16x16x32_bf16 v[76:79], v[138:141], v[220:223], v[76:79]
	v_mfma_f32_16x16x32_bf16 v[72:75], v[162:165], v[220:223], v[72:75]
	v_mfma_f32_16x16x32_bf16 v[124:127], v[158:161], v[200:203], v[124:127]
	v_mfma_f32_16x16x32_bf16 v[120:123], v[166:169], v[200:203], v[120:123]
	v_mfma_f32_16x16x32_bf16 v[108:111], v[158:161], v[208:211], v[108:111]
	v_mfma_f32_16x16x32_bf16 v[104:107], v[166:169], v[208:211], v[104:107]
	v_mfma_f32_16x16x32_bf16 v[92:95], v[158:161], v[216:219], v[92:95]
	v_mfma_f32_16x16x32_bf16 v[88:91], v[166:169], v[216:219], v[88:91]
	v_mfma_f32_16x16x32_bf16 v[76:79], v[158:161], v[234:237], v[76:79]
	v_mfma_f32_16x16x32_bf16 v[72:75], v[166:169], v[234:237], v[72:75]
	s_setprio 0
	s_setprio 1
	v_mfma_f32_16x16x32_bf16 v[116:119], v[170:173], v[186:189], v[116:119]
	v_mfma_f32_16x16x32_bf16 v[112:115], v[178:181], v[186:189], v[112:115]
	v_mfma_f32_16x16x32_bf16 v[100:103], v[170:173], v[204:207], v[100:103]
	v_mfma_f32_16x16x32_bf16 v[96:99], v[178:181], v[204:207], v[96:99]
	v_mfma_f32_16x16x32_bf16 v[84:87], v[170:173], v[212:215], v[84:87]
	v_mfma_f32_16x16x32_bf16 v[80:83], v[178:181], v[212:215], v[80:83]
	v_mfma_f32_16x16x32_bf16 v[68:71], v[170:173], v[220:223], v[68:71]
	v_mfma_f32_16x16x32_bf16 v[64:67], v[178:181], v[220:223], v[64:67]
	v_mfma_f32_16x16x32_bf16 v[116:119], v[174:177], v[200:203], v[116:119]
	v_mfma_f32_16x16x32_bf16 v[112:115], v[182:185], v[200:203], v[112:115]
	v_mfma_f32_16x16x32_bf16 v[100:103], v[174:177], v[208:211], v[100:103]
	v_mfma_f32_16x16x32_bf16 v[96:99], v[182:185], v[208:211], v[96:99]
	v_mfma_f32_16x16x32_bf16 v[84:87], v[174:177], v[216:219], v[84:87]
	v_mfma_f32_16x16x32_bf16 v[80:83], v[182:185], v[216:219], v[80:83]
	v_mfma_f32_16x16x32_bf16 v[68:71], v[174:177], v[234:237], v[68:71]
	v_mfma_f32_16x16x32_bf16 v[64:67], v[182:185], v[234:237], v[64:67]
	s_setprio 0
	s_barrier
; #define PG8_STAGE(bufoff, gbase, voff) do { _Pragma("unroll") for (int _i = 0; _i < 2; ++_i) \
;         __builtin_amdgcn_global_load_lds((const unsigned*)((const char*)(gbase) + (voff)[_i]), (PG8_LAS unsigned*)(lds + (bufoff) + ldsw + _i * 8192), 16, 0, 0); } while (0)
; #define PG8_LDA(dst, b, h) do { _Pragma("unroll") for (int m = 0; m < 4; ++m) _Pragma("unroll") for (int k = 0; k < 2; ++k) dst[m][k] = *(const PG8_LAS bf16x8*)(lds + PG8_SA(b, h) + aoff + m * 2048 + k * 1024); } while (0)
; #define PG8_MMA(ai, bj, At, Bt) do { __builtin_amdgcn_s_setprio(1); _Pragma("unroll") for (int m = 0; m < 4; ++m) _Pragma("unroll") for (int n = 0; n < 2; ++n) _Pragma("unroll") for (int k = 0; k < 2; ++k) \
;         acc[ai][bj][m][n] = __builtin_amdgcn_mfma_f32_16x16x32_bf16(Bt[n][k], At[m][k], acc[ai][bj][m][n], 0, 0, 0); __builtin_amdgcn_s_setprio(0); } while (0)
; #define PG8_WAIT_V(n) asm volatile("s_waitcnt vmcnt(" #n ")" ::: "memory")
; #define PG8_WAIT_L(n) asm volatile("s_waitcnt lgkmcnt(" #n ")" ::: "memory")
; #define PG8_BAR __builtin_amdgcn_s_barrier()
; #define PG8_SCHED __builtin_amdgcn_sched_barrier(0)
; template <class Epi, class Sched, bool ALIGN_EPI = false, bool SP2 = false>
; __device__ __forceinline__ void gemm_phase(PG8_LAS unsigned char* lds, const Gemm g, const Sched& S, const Epi& E, const int tid) {
;     ...
;             PG8_LDA(At, 1, 1); PG8_STAGE(PG8_SB(1, 0), b3, voffB); PG8_STAGE(PG8_SB(1, 1), b3 + hstepB, voffB); PG8_STAGE(PG8_SA(1, 0), a3, voffA);
;             PG8_WAIT_V(8); PG8_WAIT_L(0); PG8_BAR; PG8_MMA(1, 0, At, B0); PG8_MMA(1, 1, At, B1); PG8_BAR; PG8_SCHED;
;     ...
;         if constexpr (ALIGN_EPI) { if (wr == 0) PG8_BAR; }
	s_add_i32 s42, s48, s65
	v_lshl_add_u64 v[142:143], v[142:143], 0, s[60:61]
	s_mov_b32 m0, s42
	ds_read_b128 v[186:189], v157 offset:49152
	ds_read_b128 v[200:203], v157 offset:50176
	ds_read_b128 v[204:207], v157 offset:51200
	ds_read_b128 v[208:211], v157 offset:52224
	ds_read_b128 v[212:215], v157 offset:53248
	ds_read_b128 v[216:219], v157 offset:54272
	ds_read_b128 v[220:223], v157 offset:55296
	ds_read_b128 v[234:237], v157 offset:56320
	global_load_lds_dwordx4 v[142:143], off
	v_lshl_add_u64 v[142:143], v[190:191], 0, s[60:61]
	s_add_i32 m0, s42, 0x2000
	s_add_i32 s42, s49, s65
	global_load_lds_dwordx4 v[142:143], off
	v_lshl_add_u64 v[142:143], v[238:239], 0, s[60:61]
	s_mov_b32 m0, s42
	s_nop 0
	global_load_lds_dwordx4 v[142:143], off
	v_lshl_add_u64 v[142:143], v[240:241], 0, s[60:61]
	s_add_i32 m0, s42, 0x2000
	s_nop 0
	global_load_lds_dwordx4 v[142:143], off
	v_lshl_add_u64 v[142:143], v[242:243], 0, s[60:61]
	s_mov_b32 m0, s85
	s_nop 0
	global_load_lds_dwordx4 v[142:143], off
	v_lshl_add_u64 v[142:143], v[244:245], 0, s[60:61]
	s_mov_b32 m0, s86
	s_nop 0
	global_load_lds_dwordx4 v[142:143], off
	s_waitcnt vmcnt(8) lgkmcnt(0)
	s_setprio 1
	s_barrier
	v_mfma_f32_16x16x32_bf16 v[60:63], v[138:141], v[186:189], v[60:63]
	v_mfma_f32_16x16x32_bf16 v[56:59], v[162:165], v[186:189], v[56:59]
	v_mfma_f32_16x16x32_bf16 v[44:47], v[138:141], v[204:207], v[44:47]
	v_mfma_f32_16x16x32_bf16 v[40:43], v[162:165], v[204:207], v[40:43]
	v_mfma_f32_16x16x32_bf16 v[28:31], v[138:141], v[212:215], v[28:31]
	v_mfma_f32_16x16x32_bf16 v[24:27], v[162:165], v[212:215], v[24:27]
	v_mfma_f32_16x16x32_bf16 v[12:15], v[138:141], v[220:223], v[12:15]
	v_mfma_f32_16x16x32_bf16 v[8:11], v[162:165], v[220:223], v[8:11]
	v_mfma_f32_16x16x32_bf16 v[60:63], v[158:161], v[200:203], v[60:63]
	v_mfma_f32_16x16x32_bf16 v[56:59], v[166:169], v[200:203], v[56:59]
	v_mfma_f32_16x16x32_bf16 v[44:47], v[158:161], v[208:211], v[44:47]
	v_mfma_f32_16x16x32_bf16 v[40:43], v[166:169], v[208:211], v[40:43]
	v_mfma_f32_16x16x32_bf16 v[28:31], v[158:161], v[216:219], v[28:31]
	v_mfma_f32_16x16x32_bf16 v[24:27], v[166:169], v[216:219], v[24:27]
	v_mfma_f32_16x16x32_bf16 v[12:15], v[158:161], v[234:237], v[12:15]
	v_mfma_f32_16x16x32_bf16 v[8:11], v[166:169], v[234:237], v[8:11]
	s_setprio 0
	s_setprio 1
	v_mfma_f32_16x16x32_bf16 v[52:55], v[170:173], v[186:189], v[52:55]
	v_mfma_f32_16x16x32_bf16 v[48:51], v[178:181], v[186:189], v[48:51]
	v_mfma_f32_16x16x32_bf16 v[36:39], v[170:173], v[204:207], v[36:39]
	v_mfma_f32_16x16x32_bf16 v[32:35], v[178:181], v[204:207], v[32:35]
	v_mfma_f32_16x16x32_bf16 v[20:23], v[170:173], v[212:215], v[20:23]
	v_mfma_f32_16x16x32_bf16 v[16:19], v[178:181], v[212:215], v[16:19]
	v_mfma_f32_16x16x32_bf16 v[4:7], v[170:173], v[220:223], v[4:7]
	v_mfma_f32_16x16x32_bf16 v[0:3], v[178:181], v[220:223], v[0:3]
	v_mfma_f32_16x16x32_bf16 v[52:55], v[174:177], v[200:203], v[52:55]
	v_mfma_f32_16x16x32_bf16 v[48:51], v[182:185], v[200:203], v[48:51]
	v_mfma_f32_16x16x32_bf16 v[36:39], v[174:177], v[208:211], v[36:39]
	v_mfma_f32_16x16x32_bf16 v[32:35], v[182:185], v[208:211], v[32:35]
	v_mfma_f32_16x16x32_bf16 v[20:23], v[174:177], v[216:219], v[20:23]
	v_mfma_f32_16x16x32_bf16 v[16:19], v[182:185], v[216:219], v[16:19]
	v_mfma_f32_16x16x32_bf16 v[4:7], v[174:177], v[234:237], v[4:7]
	v_mfma_f32_16x16x32_bf16 v[0:3], v[182:185], v[234:237], v[0:3]
	s_setprio 0
	s_barrier
	s_add_u32 s24, s24, 0x100
	s_addc_u32 s25, s25, 0
	s_cmp_ge_u32 vcc_lo, s84
	s_mov_b64 s[48:49], s[50:51]
	s_mov_b32 s52, vcc_lo
	s_cbranch_scc0 .LBB0_248
	s_and_b64 vcc, exec, s[18:19]
	s_cbranch_vccz .LBB0_251
	s_barrier

; #define PG8_STAGE(bufoff, gbase, voff) do { _Pragma("unroll") for (int _i = 0; _i < 2; ++_i) \
;         __builtin_amdgcn_global_load_lds((const unsigned*)((const char*)(gbase) + (voff)[_i]), (PG8_LAS unsigned*)(lds + (bufoff) + ldsw + _i * 8192), 16, 0, 0); } while (0)
; #define PG8_LDA(dst, b, h) do { _Pragma("unroll") for (int m = 0; m < 4; ++m) _Pragma("unroll") for (int k = 0; k < 2; ++k) dst[m][k] = *(const PG8_LAS bf16x8*)(lds + PG8_SA(b, h) + aoff + m * 2048 + k * 1024); } while (0)
; #define PG8_LDB(dst, b, h) do { _Pragma("unroll") for (int n = 0; n < 2; ++n) _Pragma("unroll") for (int k = 0; k < 2; ++k) dst[n][k] = *(const PG8_LAS bf16x8*)(lds + PG8_SB(b, h) + boff + n * 2048 + k * 1024); } while (0)
; #define PG8_MMA(ai, bj, At, Bt) do { __builtin_amdgcn_s_setprio(1); _Pragma("unroll") for (int m = 0; m < 4; ++m) _Pragma("unroll") for (int n = 0; n < 2; ++n) _Pragma("unroll") for (int k = 0; k < 2; ++k) \
;         acc[ai][bj][m][n] = __builtin_amdgcn_mfma_f32_16x16x32_bf16(Bt[n][k], At[m][k], acc[ai][bj][m][n], 0, 0, 0); __builtin_amdgcn_s_setprio(0); } while (0)
; #define PG8_WAIT_V(n) asm volatile("s_waitcnt vmcnt(" #n ")" ::: "memory")
; #define PG8_WAIT_L(n) asm volatile("s_waitcnt lgkmcnt(" #n ")" ::: "memory")
; template <class Epi, class Sched, bool ALIGN_EPI = false, bool SP2 = false>
; __device__ __forceinline__ void gemm_phase(PG8_LAS unsigned char* lds, const Gemm g, const Sched& S, const Epi& E, const int tid) {
;     ...
;             const bool last = (t == nt - 2);
;             const char* a1 = cA + (size_t)(t + 1) * kstep;
;             const char* a2 = last ? nA : cA + (size_t)(t + 2) * kstep; const char* b2 = last ? nB : cB + (size_t)(t + 2) * kstep;
;             const char* a3 = a2 + kstep; const char* b3 = b2 + kstep;
;             if (last && has_next) S.a_ready(nxt);
;             if constexpr (SP2) {
;             PG8_LDB(B0, 0, 0); PG8_LDB(B1, 0, 1); PG8_SCHED; PG8_LDA(At, 0, 0); PG8_STAGE(PG8_SA(1, 1), a1 + hstepA, voffA);
;             PG8_WAIT_V(8); PG8_WAIT_L(0); PG8_BAR; PG8_MMA(0, 0, At, B0); PG8_MMA(0, 1, At, B1); PG8_BAR; PG8_SCHED;
;             PG8_LDA(At, 0, 1); PG8_STAGE(PG8_SB(0, 0), b2, voffB); PG8_STAGE(PG8_SB(0, 1), b2 + hstepB, voffB); PG8_STAGE(PG8_SA(0, 0), a2, voffA);
;             PG8_WAIT_V(8); PG8_WAIT_L(0); PG8_BAR; PG8_MMA(1, 0, At, B0); PG8_MMA(1, 1, At, B1); PG8_BAR; PG8_SCHED;
.LBB0_313:
	s_add_u32 s24, s50, 0xfffc0080
	s_addc_u32 s25, s51, -1
	s_add_i32 s68, 0, 0x10000
	s_cmp_eq_u32 s65, 12
	s_cselect_b32 s55, s40, s25
	s_cselect_b32 s54, s43, s24
	s_cselect_b32 s53, s39, s63
	s_cselect_b32 s52, s58, s59
	s_add_i32 s69, 0, 0x14000
	v_add_u32_e32 v154, s68, v139
	v_add_u32_e32 v170, s69, v139
	ds_read_b128 v[142:145], v154
	ds_read_b128 v[146:149], v154 offset:1024
	ds_read_b128 v[150:153], v154 offset:2048
	ds_read_b128 v[154:157], v154 offset:3072
	ds_read_b128 v[158:161], v170
	ds_read_b128 v[162:165], v170 offset:1024
	ds_read_b128 v[166:169], v170 offset:2048
	ds_read_b128 v[170:173], v170 offset:3072
	v_lshl_add_u64 v[190:191], s[50:51], 0, v[136:137]
	s_add_i32 m0, s21, 0xc000
	ds_read_b128 v[174:177], v141
	ds_read_b128 v[178:181], v141 offset:1024
	ds_read_b128 v[182:185], v141 offset:2048
	ds_read_b128 v[186:189], v141 offset:3072
	ds_read_b128 v[200:203], v141 offset:4096
	ds_read_b128 v[204:207], v141 offset:5120
	ds_read_b128 v[208:211], v141 offset:6144
	ds_read_b128 v[212:215], v141 offset:7168
	global_load_lds_dwordx4 v[190:191], off
	v_lshl_add_u64 v[190:191], s[50:51], 0, v[134:135]
	s_add_i32 m0, s21, 0xe000
	s_nop 0
	global_load_lds_dwordx4 v[190:191], off
	s_waitcnt vmcnt(8) lgkmcnt(0)
	s_setprio 1
	s_barrier
	v_mfma_f32_16x16x32_bf16 v[124:127], v[142:145], v[174:177], v[124:127]
	v_mfma_f32_16x16x32_bf16 v[120:123], v[150:153], v[174:177], v[120:123]
	v_mfma_f32_16x16x32_bf16 v[116:119], v[142:145], v[182:185], v[116:119]
	v_mfma_f32_16x16x32_bf16 v[112:115], v[150:153], v[182:185], v[112:115]
	v_mfma_f32_16x16x32_bf16 v[100:103], v[142:145], v[200:203], v[100:103]
	v_mfma_f32_16x16x32_bf16 v[96:99], v[150:153], v[200:203], v[96:99]
	v_mfma_f32_16x16x32_bf16 v[84:87], v[142:145], v[208:211], v[84:87]
	v_mfma_f32_16x16x32_bf16 v[80:83], v[150:153], v[208:211], v[80:83]
	v_mfma_f32_16x16x32_bf16 v[124:127], v[146:149], v[178:181], v[124:127]
	v_mfma_f32_16x16x32_bf16 v[120:123], v[154:157], v[178:181], v[120:123]
	v_mfma_f32_16x16x32_bf16 v[116:119], v[146:149], v[186:189], v[116:119]
	v_mfma_f32_16x16x32_bf16 v[112:115], v[154:157], v[186:189], v[112:115]
	v_mfma_f32_16x16x32_bf16 v[100:103], v[146:149], v[204:207], v[100:103]
	v_mfma_f32_16x16x32_bf16 v[96:99], v[154:157], v[204:207], v[96:99]
	v_mfma_f32_16x16x32_bf16 v[84:87], v[146:149], v[212:215], v[84:87]
	v_mfma_f32_16x16x32_bf16 v[80:83], v[154:157], v[212:215], v[80:83]
	s_setprio 0
	s_setprio 1
	v_mfma_f32_16x16x32_bf16 v[108:111], v[158:161], v[174:177], v[108:111]
	v_mfma_f32_16x16x32_bf16 v[104:107], v[166:169], v[174:177], v[104:107]
	v_mfma_f32_16x16x32_bf16 v[92:95], v[158:161], v[182:185], v[92:95]
	v_mfma_f32_16x16x32_bf16 v[88:91], v[166:169], v[182:185], v[88:91]
	v_mfma_f32_16x16x32_bf16 v[76:79], v[158:161], v[200:203], v[76:79]
	v_mfma_f32_16x16x32_bf16 v[72:75], v[166:169], v[200:203], v[72:75]
	v_mfma_f32_16x16x32_bf16 v[68:71], v[158:161], v[208:211], v[68:71]
	v_mfma_f32_16x16x32_bf16 v[64:67], v[166:169], v[208:211], v[64:67]
	v_mfma_f32_16x16x32_bf16 v[108:111], v[162:165], v[178:181], v[108:111]
	v_mfma_f32_16x16x32_bf16 v[104:107], v[170:173], v[178:181], v[104:107]
	v_mfma_f32_16x16x32_bf16 v[92:95], v[162:165], v[186:189], v[92:95]
	v_mfma_f32_16x16x32_bf16 v[88:91], v[170:173], v[186:189], v[88:91]
	v_mfma_f32_16x16x32_bf16 v[76:79], v[162:165], v[204:207], v[76:79]
	v_mfma_f32_16x16x32_bf16 v[72:75], v[170:173], v[204:207], v[72:75]
	v_mfma_f32_16x16x32_bf16 v[68:71], v[162:165], v[212:215], v[68:71]
	v_mfma_f32_16x16x32_bf16 v[64:67], v[170:173], v[212:215], v[64:67]
	s_setprio 0
	s_barrier
	s_add_i32 s24, s68, s20
	v_lshl_add_u64 v[190:191], s[52:53], 0, v[192:193]
	s_mov_b32 m0, s24
	ds_read_b128 v[174:177], v141 offset:16384
	ds_read_b128 v[178:181], v141 offset:17408
	ds_read_b128 v[182:185], v141 offset:18432
	ds_read_b128 v[186:189], v141 offset:19456
	ds_read_b128 v[200:203], v141 offset:20480
	ds_read_b128 v[204:207], v141 offset:21504
	ds_read_b128 v[208:211], v141 offset:22528
	ds_read_b128 v[212:215], v141 offset:23552
	global_load_lds_dwordx4 v[190:191], off
	s_add_i32 m0, s24, 0x2000
	s_add_u32 s24, s52, 0x40000
	v_lshl_add_u64 v[216:217], s[52:53], 0, v[128:129]
	s_addc_u32 s25, s53, 0
	s_add_i32 s68, s69, s20
	global_load_lds_dwordx4 v[216:217], off
	v_lshl_add_u64 v[218:219], s[24:25], 0, v[192:193]
	s_mov_b32 m0, s68
	v_lshl_add_u64 v[220:221], s[54:55], 0, v[130:131]
	global_load_lds_dwordx4 v[218:219], off
	v_lshl_add_u64 v[218:219], s[24:25], 0, v[128:129]
	s_add_i32 m0, s68, 0x2000
	s_nop 0
	global_load_lds_dwordx4 v[218:219], off
	v_lshl_add_u64 v[218:219], s[54:55], 0, v[132:133]
	s_mov_b32 m0, s21
	s_nop 0
	global_load_lds_dwordx4 v[218:219], off
	s_mov_b32 m0, s26
	s_nop 0
	global_load_lds_dwordx4 v[220:221], off
	s_waitcnt vmcnt(8) lgkmcnt(0)
	s_setprio 1
	s_barrier
; #define PG8_STAGE(bufoff, gbase, voff) do { _Pragma("unroll") for (int _i = 0; _i < 2; ++_i) \
;         __builtin_amdgcn_global_load_lds((const unsigned*)((const char*)(gbase) + (voff)[_i]), (PG8_LAS unsigned*)(lds + (bufoff) + ldsw + _i * 8192), 16, 0, 0); } while (0)
; #define PG8_LDA(dst, b, h) do { _Pragma("unroll") for (int m = 0; m < 4; ++m) _Pragma("unroll") for (int k = 0; k < 2; ++k) dst[m][k] = *(const PG8_LAS bf16x8*)(lds + PG8_SA(b, h) + aoff + m * 2048 + k * 1024); } while (0)
; #define PG8_LDB(dst, b, h) do { _Pragma("unroll") for (int n = 0; n < 2; ++n) _Pragma("unroll") for (int k = 0; k < 2; ++k) dst[n][k] = *(const PG8_LAS bf16x8*)(lds + PG8_SB(b, h) + boff + n * 2048 + k * 1024); } while (0)
; #define PG8_MMA(ai, bj, At, Bt) do { __builtin_amdgcn_s_setprio(1); _Pragma("unroll") for (int m = 0; m < 4; ++m) _Pragma("unroll") for (int n = 0; n < 2; ++n) _Pragma("unroll") for (int k = 0; k < 2; ++k) \
;         acc[ai][bj][m][n] = __builtin_amdgcn_mfma_f32_16x16x32_bf16(Bt[n][k], At[m][k], acc[ai][bj][m][n], 0, 0, 0); __builtin_amdgcn_s_setprio(0); } while (0)
; #define PG8_WAIT_V(n) asm volatile("s_waitcnt vmcnt(" #n ")" ::: "memory")
; #define PG8_WAIT_L(n) asm volatile("s_waitcnt lgkmcnt(" #n ")" ::: "memory")
; #define PG8_BAR __builtin_amdgcn_s_barrier()
; #define PG8_SCHED __builtin_amdgcn_sched_barrier(0)
; template <class Epi, class Sched, bool ALIGN_EPI = false, bool SP2 = false>
; __device__ __forceinline__ void gemm_phase(PG8_LAS unsigned char* lds, const Gemm g, const Sched& S, const Epi& E, const int tid) {
;     ...
;             PG8_WAIT_V(8); PG8_WAIT_L(0); PG8_BAR; PG8_MMA(1, 0, At, B0); PG8_MMA(1, 1, At, B1); PG8_BAR; PG8_SCHED;
;             PG8_LDB(B0, 1, 0); PG8_LDB(B1, 1, 1); PG8_SCHED; PG8_LDA(At, 1, 0); PG8_STAGE(PG8_SA(0, 1), a2 + hstepA, voffA);
;             PG8_WAIT_V(8); PG8_WAIT_L(0); PG8_BAR; PG8_MMA(0, 0, At, B0); PG8_MMA(0, 1, At, B1); PG8_BAR; PG8_SCHED;
	v_mfma_f32_16x16x32_bf16 v[60:63], v[142:145], v[174:177], v[60:63]
	v_mfma_f32_16x16x32_bf16 v[56:59], v[150:153], v[174:177], v[56:59]
	v_mfma_f32_16x16x32_bf16 v[52:55], v[142:145], v[182:185], v[52:55]
	v_mfma_f32_16x16x32_bf16 v[48:51], v[150:153], v[182:185], v[48:51]
	v_mfma_f32_16x16x32_bf16 v[36:39], v[142:145], v[200:203], v[36:39]
	v_mfma_f32_16x16x32_bf16 v[32:35], v[150:153], v[200:203], v[32:35]
	v_mfma_f32_16x16x32_bf16 v[20:23], v[142:145], v[208:211], v[20:23]
	v_mfma_f32_16x16x32_bf16 v[16:19], v[150:153], v[208:211], v[16:19]
	v_mfma_f32_16x16x32_bf16 v[60:63], v[146:149], v[178:181], v[60:63]
	v_mfma_f32_16x16x32_bf16 v[56:59], v[154:157], v[178:181], v[56:59]
	v_mfma_f32_16x16x32_bf16 v[52:55], v[146:149], v[186:189], v[52:55]
	v_mfma_f32_16x16x32_bf16 v[48:51], v[154:157], v[186:189], v[48:51]
	v_mfma_f32_16x16x32_bf16 v[36:39], v[146:149], v[204:207], v[36:39]
	v_mfma_f32_16x16x32_bf16 v[32:35], v[154:157], v[204:207], v[32:35]
	v_mfma_f32_16x16x32_bf16 v[20:23], v[146:149], v[212:215], v[20:23]
	v_mfma_f32_16x16x32_bf16 v[16:19], v[154:157], v[212:215], v[16:19]
	s_setprio 0
	s_setprio 1
	v_mfma_f32_16x16x32_bf16 v[44:47], v[158:161], v[174:177], v[44:47]
	v_mfma_f32_16x16x32_bf16 v[40:43], v[166:169], v[174:177], v[40:43]
	v_mfma_f32_16x16x32_bf16 v[28:31], v[158:161], v[182:185], v[28:31]
	v_mfma_f32_16x16x32_bf16 v[24:27], v[166:169], v[182:185], v[24:27]
	v_mfma_f32_16x16x32_bf16 v[12:15], v[158:161], v[200:203], v[12:15]
	v_mfma_f32_16x16x32_bf16 v[8:11], v[166:169], v[200:203], v[8:11]
	v_mfma_f32_16x16x32_bf16 v[4:7], v[158:161], v[208:211], v[4:7]
	v_mfma_f32_16x16x32_bf16 v[0:3], v[166:169], v[208:211], v[0:3]
	v_mfma_f32_16x16x32_bf16 v[44:47], v[162:165], v[178:181], v[44:47]
	v_mfma_f32_16x16x32_bf16 v[40:43], v[170:173], v[178:181], v[40:43]
	v_mfma_f32_16x16x32_bf16 v[28:31], v[162:165], v[186:189], v[28:31]
	v_mfma_f32_16x16x32_bf16 v[24:27], v[170:173], v[186:189], v[24:27]
	v_mfma_f32_16x16x32_bf16 v[12:15], v[162:165], v[204:207], v[12:15]
	v_mfma_f32_16x16x32_bf16 v[8:11], v[170:173], v[204:207], v[8:11]
	v_mfma_f32_16x16x32_bf16 v[4:7], v[162:165], v[212:215], v[4:7]
	v_mfma_f32_16x16x32_bf16 v[0:3], v[170:173], v[212:215], v[0:3]
	s_setprio 0
	s_barrier
	s_add_i32 s68, 0, 0x18000
	s_add_i32 s69, 0, 0x1c000
	v_add_u32_e32 v154, s68, v139
	v_add_u32_e32 v170, s69, v139
	ds_read_b128 v[142:145], v154
	ds_read_b128 v[146:149], v154 offset:1024
	ds_read_b128 v[150:153], v154 offset:2048
	ds_read_b128 v[154:157], v154 offset:3072
	ds_read_b128 v[158:161], v170
	ds_read_b128 v[162:165], v170 offset:1024
	ds_read_b128 v[166:169], v170 offset:2048
	ds_read_b128 v[170:173], v170 offset:3072
	s_add_u32 s24, s54, 0x40000
	s_addc_u32 s25, s55, 0
	s_mov_b32 m0, s27
	v_lshl_add_u64 v[222:223], s[24:25], 0, v[132:133]
	ds_read_b128 v[174:177], v141 offset:32768
	ds_read_b128 v[178:181], v141 offset:33792
	ds_read_b128 v[182:185], v141 offset:34816
	ds_read_b128 v[186:189], v141 offset:35840
	ds_read_b128 v[200:203], v141 offset:36864
	ds_read_b128 v[204:207], v141 offset:37888
	ds_read_b128 v[208:211], v141 offset:38912
	ds_read_b128 v[212:215], v141 offset:39936
	global_load_lds_dwordx4 v[222:223], off
	v_lshl_add_u64 v[222:223], s[24:25], 0, v[130:131]
	s_mov_b32 m0, s28
	s_nop 0
	global_load_lds_dwordx4 v[222:223], off
	s_waitcnt vmcnt(8) lgkmcnt(0)
	s_setprio 1
	s_barrier
	v_mfma_f32_16x16x32_bf16 v[124:127], v[142:145], v[174:177], v[124:127]
	v_mfma_f32_16x16x32_bf16 v[120:123], v[150:153], v[174:177], v[120:123]
	v_mfma_f32_16x16x32_bf16 v[116:119], v[142:145], v[182:185], v[116:119]
	v_mfma_f32_16x16x32_bf16 v[112:115], v[150:153], v[182:185], v[112:115]
	v_mfma_f32_16x16x32_bf16 v[100:103], v[142:145], v[200:203], v[100:103]
	v_mfma_f32_16x16x32_bf16 v[96:99], v[150:153], v[200:203], v[96:99]
	v_mfma_f32_16x16x32_bf16 v[84:87], v[142:145], v[208:211], v[84:87]
	v_mfma_f32_16x16x32_bf16 v[80:83], v[150:153], v[208:211], v[80:83]
	v_mfma_f32_16x16x32_bf16 v[124:127], v[146:149], v[178:181], v[124:127]
	v_mfma_f32_16x16x32_bf16 v[120:123], v[154:157], v[178:181], v[120:123]
	v_mfma_f32_16x16x32_bf16 v[116:119], v[146:149], v[186:189], v[116:119]
	v_mfma_f32_16x16x32_bf16 v[112:115], v[154:157], v[186:189], v[112:115]
	v_mfma_f32_16x16x32_bf16 v[100:103], v[146:149], v[204:207], v[100:103]
	v_mfma_f32_16x16x32_bf16 v[96:99], v[154:157], v[204:207], v[96:99]
	v_mfma_f32_16x16x32_bf16 v[84:87], v[146:149], v[212:215], v[84:87]
	v_mfma_f32_16x16x32_bf16 v[80:83], v[154:157], v[212:215], v[80:83]
	s_setprio 0
	s_setprio 1
	v_mfma_f32_16x16x32_bf16 v[108:111], v[158:161], v[174:177], v[108:111]
	v_mfma_f32_16x16x32_bf16 v[104:107], v[166:169], v[174:177], v[104:107]
	v_mfma_f32_16x16x32_bf16 v[92:95], v[158:161], v[182:185], v[92:95]
	v_mfma_f32_16x16x32_bf16 v[88:91], v[166:169], v[182:185], v[88:91]
	v_mfma_f32_16x16x32_bf16 v[76:79], v[158:161], v[200:203], v[76:79]
	v_mfma_f32_16x16x32_bf16 v[72:75], v[166:169], v[200:203], v[72:75]
	v_mfma_f32_16x16x32_bf16 v[68:71], v[158:161], v[208:211], v[68:71]
	v_mfma_f32_16x16x32_bf16 v[64:67], v[166:169], v[208:211], v[64:67]
	v_mfma_f32_16x16x32_bf16 v[108:111], v[162:165], v[178:181], v[108:111]
	v_mfma_f32_16x16x32_bf16 v[104:107], v[170:173], v[178:181], v[104:107]
	v_mfma_f32_16x16x32_bf16 v[92:95], v[162:165], v[186:189], v[92:95]
	v_mfma_f32_16x16x32_bf16 v[88:91], v[170:173], v[186:189], v[88:91]
	v_mfma_f32_16x16x32_bf16 v[76:79], v[162:165], v[204:207], v[76:79]
	v_mfma_f32_16x16x32_bf16 v[72:75], v[170:173], v[204:207], v[72:75]
	v_mfma_f32_16x16x32_bf16 v[68:71], v[162:165], v[212:215], v[68:71]
	v_mfma_f32_16x16x32_bf16 v[64:67], v[170:173], v[212:215], v[64:67]
	s_setprio 0
	s_barrier
; #define PG8_STAGE(bufoff, gbase, voff) do { _Pragma("unroll") for (int _i = 0; _i < 2; ++_i) \
;         __builtin_amdgcn_global_load_lds((const unsigned*)((const char*)(gbase) + (voff)[_i]), (PG8_LAS unsigned*)(lds + (bufoff) + ldsw + _i * 8192), 16, 0, 0); } while (0)
; #define PG8_LDA(dst, b, h) do { _Pragma("unroll") for (int m = 0; m < 4; ++m) _Pragma("unroll") for (int k = 0; k < 2; ++k) dst[m][k] = *(const PG8_LAS bf16x8*)(lds + PG8_SA(b, h) + aoff + m * 2048 + k * 1024); } while (0)
; #define PG8_MMA(ai, bj, At, Bt) do { __builtin_amdgcn_s_setprio(1); _Pragma("unroll") for (int m = 0; m < 4; ++m) _Pragma("unroll") for (int n = 0; n < 2; ++n) _Pragma("unroll") for (int k = 0; k < 2; ++k) \
;         acc[ai][bj][m][n] = __builtin_amdgcn_mfma_f32_16x16x32_bf16(Bt[n][k], At[m][k], acc[ai][bj][m][n], 0, 0, 0); __builtin_amdgcn_s_setprio(0); } while (0)
; #define PG8_WAIT_V(n) asm volatile("s_waitcnt vmcnt(" #n ")" ::: "memory")
; #define PG8_WAIT_L(n) asm volatile("s_waitcnt lgkmcnt(" #n ")" ::: "memory")
; #define PG8_BAR __builtin_amdgcn_s_barrier()
; #define PG8_SCHED __builtin_amdgcn_sched_barrier(0)
; template <class Epi, class Sched, bool ALIGN_EPI = false, bool SP2 = false>
; __device__ __forceinline__ void gemm_phase(PG8_LAS unsigned char* lds, const Gemm g, const Sched& S, const Epi& E, const int tid) {
;     ...
;             PG8_LDA(At, 1, 1); PG8_STAGE(PG8_SB(1, 0), b3, voffB); PG8_STAGE(PG8_SB(1, 1), b3 + hstepB, voffB); PG8_STAGE(PG8_SA(1, 0), a3, voffA);
;             PG8_WAIT_V(8); PG8_WAIT_L(0); PG8_BAR; PG8_MMA(1, 0, At, B0); PG8_MMA(1, 1, At, B1); PG8_BAR; PG8_SCHED;
;     ...
;         if constexpr (ALIGN_EPI) { if (wr == 0) PG8_BAR; }
	s_add_i32 s24, s68, s20
	v_lshl_add_u64 v[190:191], v[190:191], 0, s[60:61]
	s_mov_b32 m0, s24
	ds_read_b128 v[174:177], v141 offset:49152
	ds_read_b128 v[178:181], v141 offset:50176
	ds_read_b128 v[182:185], v141 offset:51200
	ds_read_b128 v[186:189], v141 offset:52224
	ds_read_b128 v[200:203], v141 offset:53248
	ds_read_b128 v[204:207], v141 offset:54272
	ds_read_b128 v[208:211], v141 offset:55296
	ds_read_b128 v[212:215], v141 offset:56320
	global_load_lds_dwordx4 v[190:191], off
	s_add_i32 m0, s24, 0x2000
	s_add_u32 s24, s52, 0x40080
	v_lshl_add_u64 v[190:191], v[216:217], 0, s[60:61]
	s_addc_u32 s25, s53, 0
	s_add_i32 s52, s69, s20
	global_load_lds_dwordx4 v[190:191], off
	v_lshl_add_u64 v[190:191], s[24:25], 0, v[192:193]
	s_mov_b32 m0, s52
	s_nop 0
	global_load_lds_dwordx4 v[190:191], off
	v_lshl_add_u64 v[190:191], s[24:25], 0, v[128:129]
	s_add_i32 m0, s52, 0x2000
	s_nop 0
	global_load_lds_dwordx4 v[190:191], off
	v_lshl_add_u64 v[190:191], v[218:219], 0, s[60:61]
	s_mov_b32 m0, s29
	s_nop 0
	global_load_lds_dwordx4 v[190:191], off
	v_lshl_add_u64 v[190:191], v[220:221], 0, s[60:61]
	s_mov_b32 m0, s36
	s_nop 0
	global_load_lds_dwordx4 v[190:191], off
	s_waitcnt vmcnt(8) lgkmcnt(0)
	s_setprio 1
	s_barrier
	v_mfma_f32_16x16x32_bf16 v[60:63], v[142:145], v[174:177], v[60:63]
	v_mfma_f32_16x16x32_bf16 v[56:59], v[150:153], v[174:177], v[56:59]
	v_mfma_f32_16x16x32_bf16 v[52:55], v[142:145], v[182:185], v[52:55]
	v_mfma_f32_16x16x32_bf16 v[48:51], v[150:153], v[182:185], v[48:51]
	v_mfma_f32_16x16x32_bf16 v[36:39], v[142:145], v[200:203], v[36:39]
	v_mfma_f32_16x16x32_bf16 v[32:35], v[150:153], v[200:203], v[32:35]
	v_mfma_f32_16x16x32_bf16 v[20:23], v[142:145], v[208:211], v[20:23]
	v_mfma_f32_16x16x32_bf16 v[16:19], v[150:153], v[208:211], v[16:19]
	v_mfma_f32_16x16x32_bf16 v[60:63], v[146:149], v[178:181], v[60:63]
	v_mfma_f32_16x16x32_bf16 v[56:59], v[154:157], v[178:181], v[56:59]
	v_mfma_f32_16x16x32_bf16 v[52:55], v[146:149], v[186:189], v[52:55]
	v_mfma_f32_16x16x32_bf16 v[48:51], v[154:157], v[186:189], v[48:51]
	v_mfma_f32_16x16x32_bf16 v[36:39], v[146:149], v[204:207], v[36:39]
	v_mfma_f32_16x16x32_bf16 v[32:35], v[154:157], v[204:207], v[32:35]
	v_mfma_f32_16x16x32_bf16 v[20:23], v[146:149], v[212:215], v[20:23]
	v_mfma_f32_16x16x32_bf16 v[16:19], v[154:157], v[212:215], v[16:19]
	s_setprio 0
	s_setprio 1
	v_mfma_f32_16x16x32_bf16 v[44:47], v[158:161], v[174:177], v[44:47]
	v_mfma_f32_16x16x32_bf16 v[40:43], v[166:169], v[174:177], v[40:43]
	v_mfma_f32_16x16x32_bf16 v[28:31], v[158:161], v[182:185], v[28:31]
	v_mfma_f32_16x16x32_bf16 v[24:27], v[166:169], v[182:185], v[24:27]
	v_mfma_f32_16x16x32_bf16 v[12:15], v[158:161], v[200:203], v[12:15]
	v_mfma_f32_16x16x32_bf16 v[8:11], v[166:169], v[200:203], v[8:11]
	v_mfma_f32_16x16x32_bf16 v[4:7], v[158:161], v[208:211], v[4:7]
	v_mfma_f32_16x16x32_bf16 v[0:3], v[166:169], v[208:211], v[0:3]
	v_mfma_f32_16x16x32_bf16 v[44:47], v[162:165], v[178:181], v[44:47]
	v_mfma_f32_16x16x32_bf16 v[40:43], v[170:173], v[178:181], v[40:43]
	v_mfma_f32_16x16x32_bf16 v[28:31], v[162:165], v[186:189], v[28:31]
	v_mfma_f32_16x16x32_bf16 v[24:27], v[170:173], v[186:189], v[24:27]
	v_mfma_f32_16x16x32_bf16 v[12:15], v[162:165], v[204:207], v[12:15]
	v_mfma_f32_16x16x32_bf16 v[8:11], v[170:173], v[204:207], v[8:11]
	v_mfma_f32_16x16x32_bf16 v[4:7], v[162:165], v[212:215], v[4:7]
	v_mfma_f32_16x16x32_bf16 v[0:3], v[170:173], v[212:215], v[0:3]
	s_setprio 0
	s_barrier
	s_add_i32 s65, s65, 2
	s_add_u32 s59, s59, 0x100
	s_addc_u32 s63, s63, 0
	s_add_u32 s50, s50, 0x100
	s_addc_u32 s51, s51, 0
	s_cmp_gt_u32 s65, 13
	s_cbranch_scc0 .LBB0_313
	s_and_b64 vcc, exec, s[14:15]
	s_cbranch_vccz .LBB0_316
	s_barrier

; #define PG8_STAGE(bufoff, gbase, voff) do { _Pragma("unroll") for (int _i = 0; _i < 2; ++_i) \
;         __builtin_amdgcn_global_load_lds((const unsigned*)((const char*)(gbase) + (voff)[_i]), (PG8_LAS unsigned*)(lds + (bufoff) + ldsw + _i * 8192), 16, 0, 0); } while (0)
; #define PG8_LDA(dst, b, h) do { _Pragma("unroll") for (int m = 0; m < 4; ++m) _Pragma("unroll") for (int k = 0; k < 2; ++k) dst[m][k] = *(const PG8_LAS bf16x8*)(lds + PG8_SA(b, h) + aoff + m * 2048 + k * 1024); } while (0)
; #define PG8_LDB(dst, b, h) do { _Pragma("unroll") for (int n = 0; n < 2; ++n) _Pragma("unroll") for (int k = 0; k < 2; ++k) dst[n][k] = *(const PG8_LAS bf16x8*)(lds + PG8_SB(b, h) + boff + n * 2048 + k * 1024); } while (0)
; #define PG8_MMA(ai, bj, At, Bt) do { __builtin_amdgcn_s_setprio(1); _Pragma("unroll") for (int m = 0; m < 4; ++m) _Pragma("unroll") for (int n = 0; n < 2; ++n) _Pragma("unroll") for (int k = 0; k < 2; ++k) \
;         acc[ai][bj][m][n] = __builtin_amdgcn_mfma_f32_16x16x32_bf16(Bt[n][k], At[m][k], acc[ai][bj][m][n], 0, 0, 0); __builtin_amdgcn_s_setprio(0); } while (0)
; #define PG8_WAIT_V(n) asm volatile("s_waitcnt vmcnt(" #n ")" ::: "memory")
; #define PG8_BAR __builtin_amdgcn_s_barrier()
; template <class Epi, class Sched, bool ALIGN_EPI = false, bool SP2 = false>
; __device__ __forceinline__ void gemm_phase(PG8_LAS unsigned char* lds, const Gemm g, const Sched& S, const Epi& E, const int tid) {
;     ...
;         for (int t = 0; t < nt; t += 2) {
;             const bool last = (t == nt - 2);
;             const char* a1 = cA + (size_t)(t + 1) * kstep;
;             const char* a2 = last ? nA : cA + (size_t)(t + 2) * kstep; const char* b2 = last ? nB : cB + (size_t)(t + 2) * kstep;
;             const char* a3 = a2 + kstep; const char* b3 = b2 + kstep;
;             if (last && has_next) S.a_ready(nxt);
;             if constexpr (SP2) {
;             PG8_LDB(B0, 0, 0); PG8_LDB(B1, 0, 1); PG8_SCHED; PG8_LDA(At, 0, 0); PG8_STAGE(PG8_SA(1, 1), a1 + hstepA, voffA);
;             PG8_WAIT_V(8); PG8_WAIT_L(0); PG8_BAR; PG8_MMA(0, 0, At, B0); PG8_MMA(0, 1, At, B1); PG8_BAR; PG8_SCHED;
;             PG8_LDA(At, 0, 1); PG8_STAGE(PG8_SB(0, 0), b2, voffB); PG8_STAGE(PG8_SB(0, 1), b2 + hstepB, voffB); PG8_STAGE(PG8_SA(0, 0), a2, voffA);
;             PG8_WAIT_V(8); PG8_WAIT_L(0); PG8_BAR; PG8_MMA(1, 0, At, B0); PG8_MMA(1, 1, At, B1); PG8_BAR; PG8_SCHED;
.LBB0_347:
	s_add_u32 s48, s10, 0x100
	s_addc_u32 s49, s11, 0
	s_add_i32 s25, 0, 0x10000
	s_cmp_eq_u32 s24, 40
	s_cselect_b32 s53, s45, s49
	s_cselect_b32 s52, s44, s48
	s_cselect_b32 s51, s47, s21
	s_cselect_b32 s50, s46, s20
	s_add_i32 s26, 0, 0x14000
	v_add_u32_e32 v72, s25, v197
	v_add_u32_e32 v92, s26, v197
	ds_read_b128 v[60:63], v72
	ds_read_b128 v[64:67], v72 offset:1024
	ds_read_b128 v[68:71], v72 offset:2048
	ds_read_b128 v[72:75], v72 offset:3072
	ds_read_b128 v[76:79], v92
	ds_read_b128 v[80:83], v92 offset:1024
	ds_read_b128 v[88:91], v92 offset:2048
	ds_read_b128 v[92:95], v92 offset:3072
	v_lshl_add_u64 v[210:211], s[10:11], 0, v[180:181]
	s_add_i32 m0, s40, 0xc000
	ds_read_b128 v[160:163], v201
	ds_read_b128 v[164:167], v201 offset:1024
	ds_read_b128 v[168:171], v201 offset:2048
	ds_read_b128 v[172:175], v201 offset:3072
	ds_read_b128 v[182:185], v201 offset:4096
	ds_read_b128 v[186:189], v201 offset:5120
	ds_read_b128 v[202:205], v201 offset:6144
	ds_read_b128 v[206:209], v201 offset:7168
	global_load_lds_dwordx4 v[210:211], off
	v_lshl_add_u64 v[210:211], s[10:11], 0, v[178:179]
	s_add_i32 m0, s40, 0xe000
	s_nop 0
	global_load_lds_dwordx4 v[210:211], off
	s_waitcnt vmcnt(8) lgkmcnt(0)
	s_setprio 1
	s_barrier
	v_mfma_f32_16x16x32_bf16 v[156:159], v[60:63], v[160:163], v[156:159]
	v_mfma_f32_16x16x32_bf16 v[152:155], v[68:71], v[160:163], v[152:155]
	v_mfma_f32_16x16x32_bf16 v[140:143], v[60:63], v[168:171], v[140:143]
	v_mfma_f32_16x16x32_bf16 v[136:139], v[68:71], v[168:171], v[136:139]
	v_mfma_f32_16x16x32_bf16 v[124:127], v[60:63], v[182:185], v[124:127]
	v_mfma_f32_16x16x32_bf16 v[120:123], v[68:71], v[182:185], v[120:123]
	v_mfma_f32_16x16x32_bf16 v[108:111], v[60:63], v[202:205], v[108:111]
	v_mfma_f32_16x16x32_bf16 v[104:107], v[68:71], v[202:205], v[104:107]
	v_mfma_f32_16x16x32_bf16 v[156:159], v[64:67], v[164:167], v[156:159]
	v_mfma_f32_16x16x32_bf16 v[152:155], v[72:75], v[164:167], v[152:155]
	v_mfma_f32_16x16x32_bf16 v[140:143], v[64:67], v[172:175], v[140:143]
	v_mfma_f32_16x16x32_bf16 v[136:139], v[72:75], v[172:175], v[136:139]
	v_mfma_f32_16x16x32_bf16 v[124:127], v[64:67], v[186:189], v[124:127]
	v_mfma_f32_16x16x32_bf16 v[120:123], v[72:75], v[186:189], v[120:123]
	v_mfma_f32_16x16x32_bf16 v[108:111], v[64:67], v[206:209], v[108:111]
	v_mfma_f32_16x16x32_bf16 v[104:107], v[72:75], v[206:209], v[104:107]
	s_setprio 0
	s_setprio 1
	v_mfma_f32_16x16x32_bf16 v[148:151], v[76:79], v[160:163], v[148:151]
	v_mfma_f32_16x16x32_bf16 v[144:147], v[88:91], v[160:163], v[144:147]
	v_mfma_f32_16x16x32_bf16 v[132:135], v[76:79], v[168:171], v[132:135]
	v_mfma_f32_16x16x32_bf16 v[128:131], v[88:91], v[168:171], v[128:131]
	v_mfma_f32_16x16x32_bf16 v[116:119], v[76:79], v[182:185], v[116:119]
	v_mfma_f32_16x16x32_bf16 v[112:115], v[88:91], v[182:185], v[112:115]
	v_mfma_f32_16x16x32_bf16 v[100:103], v[76:79], v[202:205], v[100:103]
	v_mfma_f32_16x16x32_bf16 v[96:99], v[88:91], v[202:205], v[96:99]
	v_mfma_f32_16x16x32_bf16 v[148:151], v[80:83], v[164:167], v[148:151]
	v_mfma_f32_16x16x32_bf16 v[144:147], v[92:95], v[164:167], v[144:147]
	v_mfma_f32_16x16x32_bf16 v[132:135], v[80:83], v[172:175], v[132:135]
	v_mfma_f32_16x16x32_bf16 v[128:131], v[92:95], v[172:175], v[128:131]
	v_mfma_f32_16x16x32_bf16 v[116:119], v[80:83], v[186:189], v[116:119]
	v_mfma_f32_16x16x32_bf16 v[112:115], v[92:95], v[186:189], v[112:115]
	v_mfma_f32_16x16x32_bf16 v[100:103], v[80:83], v[206:209], v[100:103]
	v_mfma_f32_16x16x32_bf16 v[96:99], v[92:95], v[206:209], v[96:99]
	s_setprio 0
	s_barrier
	s_add_i32 s10, s25, s23
	v_lshl_add_u64 v[210:211], s[50:51], 0, v[192:193]
	s_mov_b32 m0, s10
	ds_read_b128 v[160:163], v201 offset:16384
	ds_read_b128 v[164:167], v201 offset:17408
	ds_read_b128 v[168:171], v201 offset:18432
	ds_read_b128 v[172:175], v201 offset:19456
	ds_read_b128 v[182:185], v201 offset:20480
	ds_read_b128 v[186:189], v201 offset:21504
	ds_read_b128 v[202:205], v201 offset:22528
	ds_read_b128 v[206:209], v201 offset:23552
	global_load_lds_dwordx4 v[210:211], off
	s_add_i32 m0, s10, 0x2000
	s_add_u32 s10, s50, 0xb0000
	v_lshl_add_u64 v[212:213], s[50:51], 0, v[176:177]
	s_addc_u32 s11, s51, 0
	s_add_i32 s25, s26, s23
	global_load_lds_dwordx4 v[212:213], off
	v_lshl_add_u64 v[214:215], s[10:11], 0, v[192:193]
	s_mov_b32 m0, s25
	v_lshl_add_u64 v[216:217], s[52:53], 0, v[176:177]
	global_load_lds_dwordx4 v[214:215], off
	v_lshl_add_u64 v[214:215], s[10:11], 0, v[176:177]
	s_add_i32 m0, s25, 0x2000
	s_nop 0
	global_load_lds_dwordx4 v[214:215], off
	v_lshl_add_u64 v[214:215], s[52:53], 0, v[192:193]
	s_mov_b32 m0, s40
	s_nop 0
	global_load_lds_dwordx4 v[214:215], off
	s_mov_b32 m0, s54
	s_nop 0
	global_load_lds_dwordx4 v[216:217], off
	s_waitcnt vmcnt(8) lgkmcnt(0)
	s_setprio 1
	s_barrier
; #define PG8_STAGE(bufoff, gbase, voff) do { _Pragma("unroll") for (int _i = 0; _i < 2; ++_i) \
;         __builtin_amdgcn_global_load_lds((const unsigned*)((const char*)(gbase) + (voff)[_i]), (PG8_LAS unsigned*)(lds + (bufoff) + ldsw + _i * 8192), 16, 0, 0); } while (0)
; #define PG8_LDA(dst, b, h) do { _Pragma("unroll") for (int m = 0; m < 4; ++m) _Pragma("unroll") for (int k = 0; k < 2; ++k) dst[m][k] = *(const PG8_LAS bf16x8*)(lds + PG8_SA(b, h) + aoff + m * 2048 + k * 1024); } while (0)
; #define PG8_LDB(dst, b, h) do { _Pragma("unroll") for (int n = 0; n < 2; ++n) _Pragma("unroll") for (int k = 0; k < 2; ++k) dst[n][k] = *(const PG8_LAS bf16x8*)(lds + PG8_SB(b, h) + boff + n * 2048 + k * 1024); } while (0)
; #define PG8_MMA(ai, bj, At, Bt) do { __builtin_amdgcn_s_setprio(1); _Pragma("unroll") for (int m = 0; m < 4; ++m) _Pragma("unroll") for (int n = 0; n < 2; ++n) _Pragma("unroll") for (int k = 0; k < 2; ++k) \
;         acc[ai][bj][m][n] = __builtin_amdgcn_mfma_f32_16x16x32_bf16(Bt[n][k], At[m][k], acc[ai][bj][m][n], 0, 0, 0); __builtin_amdgcn_s_setprio(0); } while (0)
; #define PG8_WAIT_V(n) asm volatile("s_waitcnt vmcnt(" #n ")" ::: "memory")
; #define PG8_WAIT_L(n) asm volatile("s_waitcnt lgkmcnt(" #n ")" ::: "memory")
; #define PG8_BAR __builtin_amdgcn_s_barrier()
; #define PG8_SCHED __builtin_amdgcn_sched_barrier(0)
; template <class Epi, class Sched, bool ALIGN_EPI = false, bool SP2 = false>
; __device__ __forceinline__ void gemm_phase(PG8_LAS unsigned char* lds, const Gemm g, const Sched& S, const Epi& E, const int tid) {
;     ...
;             PG8_WAIT_V(8); PG8_WAIT_L(0); PG8_BAR; PG8_MMA(1, 0, At, B0); PG8_MMA(1, 1, At, B1); PG8_BAR; PG8_SCHED;
;             PG8_LDB(B0, 1, 0); PG8_LDB(B1, 1, 1); PG8_SCHED; PG8_LDA(At, 1, 0); PG8_STAGE(PG8_SA(0, 1), a2 + hstepA, voffA);
;             PG8_WAIT_V(8); PG8_WAIT_L(0); PG8_BAR; PG8_MMA(0, 0, At, B0); PG8_MMA(0, 1, At, B1); PG8_BAR; PG8_SCHED;
	v_mfma_f32_16x16x32_bf16 v[84:87], v[60:63], v[160:163], v[84:87]
	v_mfma_f32_16x16x32_bf16 v[56:59], v[68:71], v[160:163], v[56:59]
	v_mfma_f32_16x16x32_bf16 v[44:47], v[60:63], v[168:171], v[44:47]
	v_mfma_f32_16x16x32_bf16 v[40:43], v[68:71], v[168:171], v[40:43]
	v_mfma_f32_16x16x32_bf16 v[28:31], v[60:63], v[182:185], v[28:31]
	v_mfma_f32_16x16x32_bf16 v[24:27], v[68:71], v[182:185], v[24:27]
	v_mfma_f32_16x16x32_bf16 v[12:15], v[60:63], v[202:205], v[12:15]
	v_mfma_f32_16x16x32_bf16 v[8:11], v[68:71], v[202:205], v[8:11]
	v_mfma_f32_16x16x32_bf16 v[84:87], v[64:67], v[164:167], v[84:87]
	v_mfma_f32_16x16x32_bf16 v[56:59], v[72:75], v[164:167], v[56:59]
	v_mfma_f32_16x16x32_bf16 v[44:47], v[64:67], v[172:175], v[44:47]
	v_mfma_f32_16x16x32_bf16 v[40:43], v[72:75], v[172:175], v[40:43]
	v_mfma_f32_16x16x32_bf16 v[28:31], v[64:67], v[186:189], v[28:31]
	v_mfma_f32_16x16x32_bf16 v[24:27], v[72:75], v[186:189], v[24:27]
	v_mfma_f32_16x16x32_bf16 v[12:15], v[64:67], v[206:209], v[12:15]
	v_mfma_f32_16x16x32_bf16 v[8:11], v[72:75], v[206:209], v[8:11]
	s_setprio 0
	s_setprio 1
	v_mfma_f32_16x16x32_bf16 v[52:55], v[76:79], v[160:163], v[52:55]
	v_mfma_f32_16x16x32_bf16 v[48:51], v[88:91], v[160:163], v[48:51]
	v_mfma_f32_16x16x32_bf16 v[36:39], v[76:79], v[168:171], v[36:39]
	v_mfma_f32_16x16x32_bf16 v[32:35], v[88:91], v[168:171], v[32:35]
	v_mfma_f32_16x16x32_bf16 v[20:23], v[76:79], v[182:185], v[20:23]
	v_mfma_f32_16x16x32_bf16 v[16:19], v[88:91], v[182:185], v[16:19]
	v_mfma_f32_16x16x32_bf16 v[4:7], v[76:79], v[202:205], v[4:7]
	v_mfma_f32_16x16x32_bf16 v[0:3], v[88:91], v[202:205], v[0:3]
	v_mfma_f32_16x16x32_bf16 v[52:55], v[80:83], v[164:167], v[52:55]
	v_mfma_f32_16x16x32_bf16 v[48:51], v[92:95], v[164:167], v[48:51]
	v_mfma_f32_16x16x32_bf16 v[36:39], v[80:83], v[172:175], v[36:39]
	v_mfma_f32_16x16x32_bf16 v[32:35], v[92:95], v[172:175], v[32:35]
	v_mfma_f32_16x16x32_bf16 v[20:23], v[80:83], v[186:189], v[20:23]
	v_mfma_f32_16x16x32_bf16 v[16:19], v[92:95], v[186:189], v[16:19]
	v_mfma_f32_16x16x32_bf16 v[4:7], v[80:83], v[206:209], v[4:7]
	v_mfma_f32_16x16x32_bf16 v[0:3], v[92:95], v[206:209], v[0:3]
	s_setprio 0
	s_barrier
	s_add_i32 s25, 0, 0x18000
	s_add_i32 s26, 0, 0x1c000
	v_add_u32_e32 v72, s25, v197
	v_add_u32_e32 v92, s26, v197
	ds_read_b128 v[60:63], v72
	ds_read_b128 v[64:67], v72 offset:1024
	ds_read_b128 v[68:71], v72 offset:2048
	ds_read_b128 v[72:75], v72 offset:3072
	ds_read_b128 v[76:79], v92
	ds_read_b128 v[80:83], v92 offset:1024
	ds_read_b128 v[88:91], v92 offset:2048
	ds_read_b128 v[92:95], v92 offset:3072
	s_add_u32 s10, s52, 0xb0000
	s_addc_u32 s11, s53, 0
	s_mov_b32 m0, s55
	v_lshl_add_u64 v[218:219], s[10:11], 0, v[192:193]
	ds_read_b128 v[160:163], v201 offset:32768
	ds_read_b128 v[164:167], v201 offset:33792
	ds_read_b128 v[168:171], v201 offset:34816
	ds_read_b128 v[172:175], v201 offset:35840
	ds_read_b128 v[182:185], v201 offset:36864
	ds_read_b128 v[186:189], v201 offset:37888
	ds_read_b128 v[202:205], v201 offset:38912
	ds_read_b128 v[206:209], v201 offset:39936
	global_load_lds_dwordx4 v[218:219], off
	v_lshl_add_u64 v[218:219], s[10:11], 0, v[176:177]
	s_mov_b32 m0, s58
	s_nop 0
	global_load_lds_dwordx4 v[218:219], off
	s_waitcnt vmcnt(8) lgkmcnt(0)
	s_setprio 1
	s_barrier
	v_mfma_f32_16x16x32_bf16 v[156:159], v[60:63], v[160:163], v[156:159]
	v_mfma_f32_16x16x32_bf16 v[152:155], v[68:71], v[160:163], v[152:155]
	v_mfma_f32_16x16x32_bf16 v[140:143], v[60:63], v[168:171], v[140:143]
	v_mfma_f32_16x16x32_bf16 v[136:139], v[68:71], v[168:171], v[136:139]
	v_mfma_f32_16x16x32_bf16 v[124:127], v[60:63], v[182:185], v[124:127]
	v_mfma_f32_16x16x32_bf16 v[120:123], v[68:71], v[182:185], v[120:123]
	v_mfma_f32_16x16x32_bf16 v[108:111], v[60:63], v[202:205], v[108:111]
	v_mfma_f32_16x16x32_bf16 v[104:107], v[68:71], v[202:205], v[104:107]
	v_mfma_f32_16x16x32_bf16 v[156:159], v[64:67], v[164:167], v[156:159]
	v_mfma_f32_16x16x32_bf16 v[152:155], v[72:75], v[164:167], v[152:155]
	v_mfma_f32_16x16x32_bf16 v[140:143], v[64:67], v[172:175], v[140:143]
	v_mfma_f32_16x16x32_bf16 v[136:139], v[72:75], v[172:175], v[136:139]
	v_mfma_f32_16x16x32_bf16 v[124:127], v[64:67], v[186:189], v[124:127]
	v_mfma_f32_16x16x32_bf16 v[120:123], v[72:75], v[186:189], v[120:123]
	v_mfma_f32_16x16x32_bf16 v[108:111], v[64:67], v[206:209], v[108:111]
	v_mfma_f32_16x16x32_bf16 v[104:107], v[72:75], v[206:209], v[104:107]
	s_setprio 0
	s_setprio 1
	v_mfma_f32_16x16x32_bf16 v[148:151], v[76:79], v[160:163], v[148:151]
	v_mfma_f32_16x16x32_bf16 v[144:147], v[88:91], v[160:163], v[144:147]
	v_mfma_f32_16x16x32_bf16 v[132:135], v[76:79], v[168:171], v[132:135]
	v_mfma_f32_16x16x32_bf16 v[128:131], v[88:91], v[168:171], v[128:131]
	v_mfma_f32_16x16x32_bf16 v[116:119], v[76:79], v[182:185], v[116:119]
	v_mfma_f32_16x16x32_bf16 v[112:115], v[88:91], v[182:185], v[112:115]
	v_mfma_f32_16x16x32_bf16 v[100:103], v[76:79], v[202:205], v[100:103]
	v_mfma_f32_16x16x32_bf16 v[96:99], v[88:91], v[202:205], v[96:99]
	v_mfma_f32_16x16x32_bf16 v[148:151], v[80:83], v[164:167], v[148:151]
	v_mfma_f32_16x16x32_bf16 v[144:147], v[92:95], v[164:167], v[144:147]
	v_mfma_f32_16x16x32_bf16 v[132:135], v[80:83], v[172:175], v[132:135]
	v_mfma_f32_16x16x32_bf16 v[128:131], v[92:95], v[172:175], v[128:131]
	v_mfma_f32_16x16x32_bf16 v[116:119], v[80:83], v[186:189], v[116:119]
	v_mfma_f32_16x16x32_bf16 v[112:115], v[92:95], v[186:189], v[112:115]
	v_mfma_f32_16x16x32_bf16 v[100:103], v[80:83], v[206:209], v[100:103]
	v_mfma_f32_16x16x32_bf16 v[96:99], v[92:95], v[206:209], v[96:99]
	s_setprio 0
	s_barrier
; #define PG8_STAGE(bufoff, gbase, voff) do { _Pragma("unroll") for (int _i = 0; _i < 2; ++_i) \
;         __builtin_amdgcn_global_load_lds((const unsigned*)((const char*)(gbase) + (voff)[_i]), (PG8_LAS unsigned*)(lds + (bufoff) + ldsw + _i * 8192), 16, 0, 0); } while (0)
; #define PG8_LDA(dst, b, h) do { _Pragma("unroll") for (int m = 0; m < 4; ++m) _Pragma("unroll") for (int k = 0; k < 2; ++k) dst[m][k] = *(const PG8_LAS bf16x8*)(lds + PG8_SA(b, h) + aoff + m * 2048 + k * 1024); } while (0)
; #define PG8_MMA(ai, bj, At, Bt) do { __builtin_amdgcn_s_setprio(1); _Pragma("unroll") for (int m = 0; m < 4; ++m) _Pragma("unroll") for (int n = 0; n < 2; ++n) _Pragma("unroll") for (int k = 0; k < 2; ++k) \
;         acc[ai][bj][m][n] = __builtin_amdgcn_mfma_f32_16x16x32_bf16(Bt[n][k], At[m][k], acc[ai][bj][m][n], 0, 0, 0); __builtin_amdgcn_s_setprio(0); } while (0)
; #define PG8_WAIT_V(n) asm volatile("s_waitcnt vmcnt(" #n ")" ::: "memory")
; #define PG8_WAIT_L(n) asm volatile("s_waitcnt lgkmcnt(" #n ")" ::: "memory")
; #define PG8_BAR __builtin_amdgcn_s_barrier()
; #define PG8_SCHED __builtin_amdgcn_sched_barrier(0)
; template <class Epi, class Sched, bool ALIGN_EPI = false, bool SP2 = false>
; __device__ __forceinline__ void gemm_phase(PG8_LAS unsigned char* lds, const Gemm g, const Sched& S, const Epi& E, const int tid) {
;     ...
;         for (int t = 0; t < nt; t += 2) {
;     ...
;             PG8_LDA(At, 1, 1); PG8_STAGE(PG8_SB(1, 0), b3, voffB); PG8_STAGE(PG8_SB(1, 1), b3 + hstepB, voffB); PG8_STAGE(PG8_SA(1, 0), a3, voffA);
;             PG8_WAIT_V(8); PG8_WAIT_L(0); PG8_BAR; PG8_MMA(1, 0, At, B0); PG8_MMA(1, 1, At, B1); PG8_BAR; PG8_SCHED;
;     ...
;         if constexpr (ALIGN_EPI) { if (wr == 0) PG8_BAR; }
	s_add_i32 s10, s25, s23
	v_lshl_add_u64 v[210:211], v[210:211], 0, s[60:61]
	s_mov_b32 m0, s10
	ds_read_b128 v[160:163], v201 offset:49152
	ds_read_b128 v[164:167], v201 offset:50176
	ds_read_b128 v[168:171], v201 offset:51200
	ds_read_b128 v[172:175], v201 offset:52224
	ds_read_b128 v[182:185], v201 offset:53248
	ds_read_b128 v[186:189], v201 offset:54272
	ds_read_b128 v[202:205], v201 offset:55296
	ds_read_b128 v[206:209], v201 offset:56320
	global_load_lds_dwordx4 v[210:211], off
	s_add_i32 m0, s10, 0x2000
	s_add_u32 s10, s50, 0xb0080
	v_lshl_add_u64 v[210:211], v[212:213], 0, s[60:61]
	s_addc_u32 s11, s51, 0
	s_add_i32 s25, s26, s23
	global_load_lds_dwordx4 v[210:211], off
	v_lshl_add_u64 v[210:211], s[10:11], 0, v[192:193]
	s_mov_b32 m0, s25
	s_nop 0
	global_load_lds_dwordx4 v[210:211], off
	v_lshl_add_u64 v[210:211], s[10:11], 0, v[176:177]
	s_add_i32 m0, s25, 0x2000
	s_nop 0
	global_load_lds_dwordx4 v[210:211], off
	v_lshl_add_u64 v[210:211], v[214:215], 0, s[60:61]
	s_mov_b32 m0, s79
	s_nop 0
	global_load_lds_dwordx4 v[210:211], off
	v_lshl_add_u64 v[210:211], v[216:217], 0, s[60:61]
	s_mov_b32 m0, s80
	s_nop 0
	global_load_lds_dwordx4 v[210:211], off
	s_waitcnt vmcnt(8) lgkmcnt(0)
	s_setprio 1
	s_barrier
	v_mfma_f32_16x16x32_bf16 v[84:87], v[60:63], v[160:163], v[84:87]
	v_mfma_f32_16x16x32_bf16 v[56:59], v[68:71], v[160:163], v[56:59]
	v_mfma_f32_16x16x32_bf16 v[44:47], v[60:63], v[168:171], v[44:47]
	v_mfma_f32_16x16x32_bf16 v[40:43], v[68:71], v[168:171], v[40:43]
	v_mfma_f32_16x16x32_bf16 v[28:31], v[60:63], v[182:185], v[28:31]
	v_mfma_f32_16x16x32_bf16 v[24:27], v[68:71], v[182:185], v[24:27]
	v_mfma_f32_16x16x32_bf16 v[12:15], v[60:63], v[202:205], v[12:15]
	v_mfma_f32_16x16x32_bf16 v[8:11], v[68:71], v[202:205], v[8:11]
	v_mfma_f32_16x16x32_bf16 v[84:87], v[64:67], v[164:167], v[84:87]
	v_mfma_f32_16x16x32_bf16 v[56:59], v[72:75], v[164:167], v[56:59]
	v_mfma_f32_16x16x32_bf16 v[44:47], v[64:67], v[172:175], v[44:47]
	v_mfma_f32_16x16x32_bf16 v[40:43], v[72:75], v[172:175], v[40:43]
	v_mfma_f32_16x16x32_bf16 v[28:31], v[64:67], v[186:189], v[28:31]
	v_mfma_f32_16x16x32_bf16 v[24:27], v[72:75], v[186:189], v[24:27]
	v_mfma_f32_16x16x32_bf16 v[12:15], v[64:67], v[206:209], v[12:15]
	v_mfma_f32_16x16x32_bf16 v[8:11], v[72:75], v[206:209], v[8:11]
	s_setprio 0
	s_setprio 1
	v_mfma_f32_16x16x32_bf16 v[52:55], v[76:79], v[160:163], v[52:55]
	v_mfma_f32_16x16x32_bf16 v[48:51], v[88:91], v[160:163], v[48:51]
	v_mfma_f32_16x16x32_bf16 v[36:39], v[76:79], v[168:171], v[36:39]
	v_mfma_f32_16x16x32_bf16 v[32:35], v[88:91], v[168:171], v[32:35]
	v_mfma_f32_16x16x32_bf16 v[20:23], v[76:79], v[182:185], v[20:23]
	v_mfma_f32_16x16x32_bf16 v[16:19], v[88:91], v[182:185], v[16:19]
	v_mfma_f32_16x16x32_bf16 v[4:7], v[76:79], v[202:205], v[4:7]
	v_mfma_f32_16x16x32_bf16 v[0:3], v[88:91], v[202:205], v[0:3]
	v_mfma_f32_16x16x32_bf16 v[52:55], v[80:83], v[164:167], v[52:55]
	v_mfma_f32_16x16x32_bf16 v[48:51], v[92:95], v[164:167], v[48:51]
	v_mfma_f32_16x16x32_bf16 v[36:39], v[80:83], v[172:175], v[36:39]
	v_mfma_f32_16x16x32_bf16 v[32:35], v[92:95], v[172:175], v[32:35]
	v_mfma_f32_16x16x32_bf16 v[20:23], v[80:83], v[186:189], v[20:23]
	v_mfma_f32_16x16x32_bf16 v[16:19], v[92:95], v[186:189], v[16:19]
	v_mfma_f32_16x16x32_bf16 v[4:7], v[80:83], v[206:209], v[4:7]
	v_mfma_f32_16x16x32_bf16 v[0:3], v[92:95], v[206:209], v[0:3]
	s_setprio 0
	s_barrier
	s_add_i32 s24, s24, 2
	s_add_u32 s20, s20, 0x100
	s_addc_u32 s21, s21, 0
	s_cmp_gt_u32 s24, 41
	s_mov_b64 s[10:11], s[48:49]
	s_cbranch_scc0 .LBB0_347
	s_and_b64 vcc, exec, s[42:43]
	s_cbranch_vccz .LBB0_350
	s_barrier
